# v2: no per-segment s_setprio in the bf16 w_in GEMM loop; sc1 write-through 16B stores in P4/P10/P13; nt hint on P2 x loads
# speedup vs baseline: 1.0073x; 1.0073x over previous
; #define LAS __attribute__((address_space(3)))
; template <int OUTM, bool P16>
; __device__ __forceinline__ void norm_prompt_rows(Frame& F, const float* srcP32, const float* gain, int sub, bf16* Hd, float* yP) {
;     ...
;     for (int mb = 32 * F.vcu; mb < MP; mb += 32 * F.G) {
;         const int m0 = mb + 4 * F.wave;
;         int flane = flane0; asm volatile("" : "+v"(flane));
;         v4u raw[P16 ? RB : 1][4]; f32x4 vf[P16 ? 1 : RB][4][2];
; #pragma unroll
;         for (int r = 0; r < RB; ++r) NPR_LOAD(r, m0 + r);
;         f32x4 Am[4][2], Bm[4][2];
;         if (OUTM == 2) {
; #pragma unroll
;             for (int j = 0; j < 4; ++j)
; #pragma unroll
;                 for (int hf = 0; hf < 2; ++hf) { Am[j][hf] = *(const f32x4*)(gain + 8 * (flane + 64 * j) + 4 * hf); Bm[j][hf] = (f32x4){0.f, 0.f, 0.f, 0.f}; }
;         } else {
;             { const int k = 4 * (64 * F.wave + flane);
;                 const float* sh = WSP(float, WS_MODS) + (size_t)pg8::modrow_of(mb) * NMOD + (size_t)(3 * sub) * DM; const float* sc = sh + DM;
;                 const f32x4 g4 = *(const f32x4*)(gain + k), s0 = *(const f32x4*)(sc + k), s1 = *(const f32x4*)(sc + MODSB_DELTA + k), h0 = *(const f32x4*)(sh + k), h1 = *(const f32x4*)(sh + MODSB_DELTA + k);
;                 *(LAS f32x4*)(modA + k) = g4 * ((s0 + s1) + 1.0f); *(LAS f32x4*)(modB + k) = h0 + h1; }
;             __syncthreads();
; #pragma unroll
;             for (int j = 0; j < 4; ++j)
; #pragma unroll
;                 for (int hf = 0; hf < 2; ++hf) { const int k = 8 * (flane + 64 * j) + 4 * hf; Am[j][hf] = *(const LAS f32x4*)(modA + k); Bm[j][hf] = *(const LAS f32x4*)(modB + k); }
;         }
; #pragma unroll
;         for (int r = 0; r < 4; ++r) {
;             const int slot = r % RB;
;             float ss = 0.f;
; #pragma unroll
;             for (int j = 0; j < 4; ++j) { f32x4 x0, x1; NPR_GET(slot, j, x0, x1);
;                 ss += ((x0[0] * x0[0] + x0[1] * x0[1]) + (x0[2] * x0[2] + x0[3] * x0[3])) + ((x1[0] * x1[0] + x1[1] * x1[1]) + (x1[2] * x1[2] + x1[3] * x1[3])); }
;             const float rstd = 1.0f / sqrtf(wave_sum(ss) * (1.0f / DM) + EPS);
.LBB0_261:
	s_add_i32 s2, s11, s10
	s_ashr_i32 s3, s2, 31
	s_lshl_b64 s[0:1], s[2:3], 13
	s_add_u32 s8, s80, s0
	s_addc_u32 s9, s81, s1
	s_add_i32 s6, s2, 1
	s_ashr_i32 s7, s6, 31
	s_lshl_b64 s[0:1], s[6:7], 13
	s_add_u32 s0, s80, s0
	s_waitcnt vmcnt(1)
	v_mov_b32_e32 v32, v1
	s_addc_u32 s1, s81, s1
	s_ashr_i32 s21, s10, 11
	s_mul_hi_i32 s23, s21, 0x12000
	v_lshl_add_u32 v22, v32, 2, s16
	s_mul_i32 s21, s21, 0x12000
	s_add_u32 s22, s14, s21
	v_ashrrev_i32_e32 v23, 31, v22
	v_lshlrev_b32_e32 v130, 3, v32
	s_addc_u32 s23, s15, s23
	v_lshlrev_b64 v[18:19], 2, v[22:23]
	v_ashrrev_i32_e32 v131, 31, v130
	v_lshl_add_u64 v[14:15], s[22:23], 0, v[18:19]
	v_lshlrev_b64 v[138:139], 2, v[130:131]
	v_add_co_u32_e32 v6, vcc, s13, v14
	v_lshl_add_u64 v[2:3], s[8:9], 0, v[138:139]
	s_nop 0
	v_addc_co_u32_e32 v7, vcc, 0, v15, vcc
	global_load_dwordx4 v[106:109], v[2:3], off offset:16 nt
	global_load_dwordx4 v[110:113], v[2:3], off nt
	v_add_co_u32_e32 v2, vcc, s17, v14
	v_add_u32_e32 v136, 0x200, v130
	s_nop 0
	v_addc_co_u32_e32 v3, vcc, 0, v15, vcc
	global_load_dwordx4 v[2:5], v[2:3], off nt
	s_nop 0
	global_load_dwordx4 v[6:9], v[6:7], off nt
	s_nop 0
	global_load_dwordx4 v[10:13], v[14:15], off nt
	v_add_co_u32_e32 v14, vcc, s18, v14
	v_lshl_add_u64 v[18:19], s[52:53], 0, v[18:19]
	s_nop 0
	v_addc_co_u32_e32 v15, vcc, 0, v15, vcc
	global_load_dwordx4 v[14:17], v[14:15], off nt
	v_ashrrev_i32_e32 v137, 31, v136
	global_load_dwordx4 v[18:21], v[18:19], off nt
	v_lshlrev_b64 v[140:141], 2, v[136:137]
	v_lshl_add_u64 v[24:25], s[8:9], 0, v[140:141]
	global_load_dwordx4 v[126:129], v[24:25], off nt
	global_load_dwordx4 v[122:125], v[24:25], off offset:16 nt
	v_add_u32_e32 v132, 0x600, v130
	v_ashrrev_i32_e32 v133, 31, v132
	v_lshlrev_b64 v[142:143], 2, v[132:133]
	v_lshl_add_u64 v[24:25], s[8:9], 0, v[142:143]
	v_add_u32_e32 v134, 0x400, v130
	global_load_dwordx4 v[102:105], v[24:25], off nt
	global_load_dwordx4 v[98:101], v[24:25], off offset:16 nt
	v_ashrrev_i32_e32 v135, 31, v134
	v_lshlrev_b64 v[144:145], 2, v[134:135]
	v_lshl_add_u64 v[24:25], s[8:9], 0, v[144:145]
	global_load_dwordx4 v[118:121], v[24:25], off nt
	global_load_dwordx4 v[114:117], v[24:25], off offset:16 nt
	v_cmp_lt_i32_e32 vcc, v148, v147
	v_lshl_add_u32 v33, v22, 2, 0
	v_lshl_add_u64 v[24:25], s[0:1], 0, v[140:141]
	v_cndmask_b32_e32 v23, v146, v148, vcc
	v_lshlrev_b32_e32 v157, 2, v23
	v_lshl_add_u64 v[22:23], s[0:1], 0, v[138:139]
	v_lshl_add_u64 v[26:27], s[0:1], 0, v[144:145]
	v_lshl_add_u64 v[28:29], s[0:1], 0, v[142:143]
	global_load_dwordx4 v[90:93], v[22:23], off offset:16 nt
	global_load_dwordx4 v[94:97], v[22:23], off nt
	global_load_dwordx4 v[82:85], v[24:25], off offset:16 nt
	global_load_dwordx4 v[86:89], v[24:25], off nt
	global_load_dwordx4 v[74:77], v[26:27], off offset:16 nt
	global_load_dwordx4 v[78:81], v[26:27], off nt
	global_load_dwordx4 v[66:69], v[28:29], off offset:16 nt
	global_load_dwordx4 v[70:73], v[28:29], off nt
	v_cmp_lt_i32_e32 vcc, v149, v147
	s_waitcnt vmcnt(20)
	v_pk_mul_f32 v[26:27], v[108:109], v[108:109]
	s_waitcnt vmcnt(19)
	v_pk_mul_f32 v[22:23], v[112:113], v[112:113]
	v_pk_mul_f32 v[24:25], v[110:111], v[110:111]
	v_pk_mul_f32 v[28:29], v[106:107], v[106:107]
	v_pk_mov_b32 v[30:31], v[24:25], v[22:23] op_sel:[1,0]
	v_mov_b32_e32 v25, v23
	s_waitcnt vmcnt(17)
	v_pk_add_f32 v[8:9], v[8:9], v[4:5]
	v_pk_add_f32 v[6:7], v[6:7], v[2:3]
	v_pk_add_f32 v[8:9], v[8:9], 1.0 op_sel_hi:[1,0]
	v_pk_add_f32 v[6:7], v[6:7], 1.0 op_sel_hi:[1,0]
	v_pk_mov_b32 v[22:23], v[28:29], v[26:27] op_sel:[1,0]
	v_mov_b32_e32 v29, v27
	v_pk_add_f32 v[24:25], v[30:31], v[24:25]
	s_waitcnt vmcnt(15)
	v_pk_add_f32 v[4:5], v[12:13], v[16:17]
	v_pk_add_f32 v[2:3], v[10:11], v[14:15]
	ds_write_b128 v33, v[2:5] offset:8192
	s_waitcnt vmcnt(14)
	v_pk_mul_f32 v[4:5], v[20:21], v[8:9]
	v_pk_mul_f32 v[2:3], v[18:19], v[6:7]
	ds_write_b128 v33, v[2:5]
	s_waitcnt vmcnt(13)
	v_pk_mul_f32 v[4:5], v[128:129], v[128:129]
	v_pk_mul_f32 v[6:7], v[126:127], v[126:127]
	v_pk_add_f32 v[2:3], v[22:23], v[28:29]
	v_pk_mov_b32 v[8:9], v[6:7], v[4:5] op_sel:[1,0]
	v_mov_b32_e32 v7, v5
	v_pk_add_f32 v[4:5], v[8:9], v[6:7]
	s_waitcnt vmcnt(12)
	v_pk_mul_f32 v[6:7], v[124:125], v[124:125]
	v_pk_mul_f32 v[8:9], v[122:123], v[122:123]
	s_waitcnt vmcnt(11)
	v_mul_f32_e32 v12, v104, v104
	v_pk_mov_b32 v[10:11], v[8:9], v[6:7] op_sel:[1,0]
	v_mov_b32_e32 v9, v7
	v_pk_add_f32 v[6:7], v[10:11], v[8:9]
	v_mul_f32_e32 v10, v102, v102
	v_mul_f32_e32 v11, v103, v103
	v_mul_f32_e32 v13, v105, v105
	v_pk_add_f32 v[8:9], v[24:25], v[24:25] op_sel:[0,1] op_sel_hi:[1,0]
	v_pk_add_f32 v[2:3], v[2:3], v[2:3] op_sel:[0,1] op_sel_hi:[1,0]
	v_pk_add_f32 v[4:5], v[4:5], v[4:5] op_sel:[0,1] op_sel_hi:[1,0]
	v_pk_add_f32 v[6:7], v[6:7], v[6:7] op_sel:[0,1] op_sel_hi:[1,0]
	v_mov_b32_e32 v9, v10
	v_mov_b32_e32 v3, v11
	v_mov_b32_e32 v5, v12
	v_mov_b32_e32 v7, v13
	v_pk_add_f32 v[2:3], v[8:9], v[2:3]
	v_pk_add_f32 v[4:5], v[4:5], v[6:7]
	s_waitcnt vmcnt(9)
	v_mul_f32_e32 v6, v121, v121
	v_pk_add_f32 v[2:3], v[2:3], v[4:5]
	v_mul_f32_e32 v4, v119, v119
	v_mul_f32_e32 v14, v98, v98
	v_mul_f32_e32 v15, v99, v99
	v_pk_fma_f32 v[4:5], v[118:119], v[118:119], v[4:5] op_sel_hi:[1,1,0]
	v_pk_fma_f32 v[6:7], v[120:121], v[120:121], v[6:7] op_sel_hi:[1,1,0]
	v_mov_b32_e32 v5, v14
	v_mov_b32_e32 v7, v15
	v_pk_add_f32 v[4:5], v[4:5], v[6:7]
	s_waitcnt vmcnt(8)
	v_mul_f32_e32 v6, v115, v115
	v_mul_f32_e32 v8, v117, v117
	v_mul_f32_e32 v16, v100, v100
	v_mul_f32_e32 v17, v101, v101
	v_pk_fma_f32 v[6:7], v[114:115], v[114:115], v[6:7] op_sel_hi:[1,1,0]
	v_pk_fma_f32 v[8:9], v[116:117], v[116:117], v[8:9] op_sel_hi:[1,1,0]
	v_mov_b32_e32 v7, v16
	v_mov_b32_e32 v9, v17
	v_pk_add_f32 v[6:7], v[6:7], v[8:9]
	s_waitcnt lgkmcnt(0)
	v_pk_add_f32 v[4:5], v[4:5], v[6:7]
	v_lshl_add_u32 v6, v32, 5, 0
	v_pk_add_f32 v[2:3], v[2:3], v[4:5]
	v_cndmask_b32_e32 v4, v146, v149, vcc
	v_add_f32_e32 v2, v2, v3
	ds_bpermute_b32 v3, v157, v2
	v_lshlrev_b32_e32 v158, 2, v4
	v_cmp_lt_i32_e32 vcc, v150, v147
	s_barrier
; #define GAS __attribute__((address_space(1)))
; #define LAS __attribute__((address_space(3)))
; __device__ __forceinline__ unsigned pk2(float lo, float hi) { return f2bf(lo) | (f2bf(hi) << 16); }
; template <int OUTM, bool P16>
; __device__ __forceinline__ void norm_prompt_rows(Frame& F, const float* srcP32, const float* gain, int sub, bf16* Hd, float* yP) {
;     ...
; #pragma unroll
;             for (int j = 0; j < 4; ++j)
; #pragma unroll
;                 for (int hf = 0; hf < 2; ++hf) { const int k = 8 * (flane + 64 * j) + 4 * hf; Am[j][hf] = *(const LAS f32x4*)(modA + k); Bm[j][hf] = *(const LAS f32x4*)(modB + k); }
;         }
; #pragma unroll
;         for (int r = 0; r < 4; ++r) {
;             const int slot = r % RB;
;             float ss = 0.f;
; #pragma unroll
;             for (int j = 0; j < 4; ++j) { f32x4 x0, x1; NPR_GET(slot, j, x0, x1);
;                 ss += ((x0[0] * x0[0] + x0[1] * x0[1]) + (x0[2] * x0[2] + x0[3] * x0[3])) + ((x1[0] * x1[0] + x1[1] * x1[1]) + (x1[2] * x1[2] + x1[3] * x1[3])); }
;             const float rstd = 1.0f / sqrtf(wave_sum(ss) * (1.0f / DM) + EPS);
; #pragma unroll
;             for (int j = 0; j < 4; ++j) { const size_t o = (size_t)(m0 + r) * DM + 8 * (flane + 64 * j);
;                 f32x4 x0, x1; NPR_GET(slot, j, x0, x1);
;                 const f32x4 o0 = (x0 * rstd) * Am[j][0] + Bm[j][0], o1 = (x1 * rstd) * Am[j][1] + Bm[j][1];
;                 if (OUTM == 2) { __builtin_nontemporal_store(o0, (f32x4*)(yP + o)); __builtin_nontemporal_store(o1, (f32x4*)(yP + o + 4)); }
;                 else if (OUTM == 1) { v2u pk; pk.x = pg8::pk4_fp8(o0[0], o0[1], o0[2], o0[3]); pk.y = pg8::pk4_fp8(o1[0], o1[1], o1[2], o1[3]); *(GAS v2u*)((unsigned char*)Hd + o) = pk; }
;                 else { v4u pk; pk.x = pk2(o0[0], o0[1]); pk.y = pk2(o0[2], o0[3]); pk.z = pk2(o1[0], o1[1]); pk.w = pk2(o1[2], o1[3]); *(GAS v4u*)(Hd + o) = pk; } }
	s_waitcnt lgkmcnt(0)
	v_add_f32_e32 v2, v2, v3
	ds_bpermute_b32 v3, v158, v2
	v_cndmask_b32_e32 v4, v146, v150, vcc
	v_lshlrev_b32_e32 v159, 2, v4
	v_cmp_lt_i32_e32 vcc, v151, v147
	ds_read_b128 v[54:57], v6
	ds_read_b128 v[50:53], v6 offset:16
	s_waitcnt lgkmcnt(2)
	v_add_f32_e32 v2, v2, v3
	ds_bpermute_b32 v3, v159, v2
	v_cndmask_b32_e32 v4, v146, v151, vcc
	v_lshlrev_b32_e32 v160, 2, v4
	v_cmp_lt_i32_e32 vcc, v152, v147
	ds_read_b128 v[62:65], v6 offset:8192
	ds_read_b128 v[58:61], v6 offset:8208
	s_waitcnt lgkmcnt(2)
	v_add_f32_e32 v2, v2, v3
	ds_bpermute_b32 v3, v160, v2
	v_cndmask_b32_e32 v4, v146, v152, vcc
	v_lshlrev_b32_e32 v161, 2, v4
	v_cmp_lt_i32_e32 vcc, v153, v147
	ds_read_b128 v[42:45], v6 offset:2048
	ds_read_b128 v[34:37], v6 offset:2064
	ds_read_b128 v[46:49], v6 offset:10240
	ds_read_b128 v[38:41], v6 offset:10256
	s_waitcnt lgkmcnt(4)
	v_add_f32_e32 v2, v2, v3
	ds_bpermute_b32 v3, v161, v2
	v_cndmask_b32_e32 v4, v146, v153, vcc
	v_lshlrev_b32_e32 v162, 2, v4
	ds_read_b128 v[26:29], v6 offset:4096
	ds_read_b128 v[18:21], v6 offset:4112
	ds_read_b128 v[30:33], v6 offset:12288
	ds_read_b128 v[22:25], v6 offset:12304
	s_waitcnt lgkmcnt(4)
	v_add_f32_e32 v2, v2, v3
	ds_bpermute_b32 v3, v162, v2
	s_waitcnt lgkmcnt(0)
	v_add_f32_e32 v2, v2, v3
	v_fmamk_f32 v2, v2, 0x3a000000, v154
	v_mul_f32_e32 v3, 0x4f800000, v2
	v_cmp_gt_f32_e32 vcc, s19, v2
	s_nop 1
	v_cndmask_b32_e32 v2, v2, v3, vcc
	v_sqrt_f32_e32 v3, v2
	s_nop 0
	v_add_u32_e32 v4, -1, v3
	v_fma_f32 v5, -v4, v3, v2
	v_cmp_ge_f32_e64 s[0:1], 0, v5
	v_add_u32_e32 v5, 1, v3
	s_nop 0
	v_cndmask_b32_e64 v4, v3, v4, s[0:1]
	v_fma_f32 v3, -v5, v3, v2
	v_cmp_lt_f32_e64 s[0:1], 0, v3
	s_nop 1
	v_cndmask_b32_e64 v3, v4, v5, s[0:1]
	v_mul_f32_e32 v4, 0x37800000, v3
	v_cndmask_b32_e32 v3, v3, v4, vcc
	v_cmp_class_f32_e32 vcc, v2, v155
	s_nop 1
	v_cndmask_b32_e32 v163, v3, v2, vcc
	v_div_scale_f32 v164, s[0:1], v163, v163, 1.0
	v_rcp_f32_e32 v165, v164
	s_lshl_b64 s[0:1], s[2:3], 11
	s_add_u32 s0, s4, s0
	s_addc_u32 s1, s5, s1
	v_fma_f32 v166, -v164, v165, 1.0
	v_fmac_f32_e32 v165, v166, v165
	v_div_scale_f32 v166, vcc, 1.0, v163, 1.0
	v_mul_f32_e32 v167, v166, v165
	v_fma_f32 v168, -v164, v167, v166
	v_fmac_f32_e32 v167, v168, v165
	v_fma_f32 v164, -v164, v167, v166
	v_div_fmas_f32 v164, v164, v165, v167
	v_div_fixup_f32 v164, v164, v163, 1.0
	v_pk_mul_f32 v[110:111], v[110:111], v[164:165] op_sel_hi:[1,0]
	v_pk_mul_f32 v[106:107], v[106:107], v[164:165] op_sel_hi:[1,0]
	v_pk_fma_f32 v[110:111], v[54:55], v[110:111], v[62:63]
	v_pk_fma_f32 v[106:107], v[50:51], v[106:107], v[58:59]
	v_med3_f32 v163, v110, s20, v156
	v_med3_f32 v111, v111, s20, v156
	v_mov_b32_e32 v110, 0
	v_cvt_pk_fp8_f32 v110, v163, v111
	v_med3_f32 v106, v106, s20, v156
	v_med3_f32 v107, v107, s20, v156
	v_mov_b32_e32 v111, 0
	v_cvt_pk_fp8_f32 v111, v106, v107
	v_pk_mul_f32 v[108:109], v[108:109], v[164:165] op_sel_hi:[1,0]
	v_pk_mul_f32 v[112:113], v[112:113], v[164:165] op_sel_hi:[1,0]
	v_pk_fma_f32 v[108:109], v[52:53], v[108:109], v[60:61]
	v_pk_fma_f32 v[112:113], v[56:57], v[112:113], v[64:65]
	v_med3_f32 v106, v108, s20, v156
	v_med3_f32 v107, v109, s20, v156
	v_med3_f32 v112, v112, s20, v156
	v_med3_f32 v113, v113, s20, v156
	v_cvt_pk_fp8_f32 v111, v106, v107 op_sel:[0,0,1]
	v_pk_mul_f32 v[106:107], v[126:127], v[164:165] op_sel_hi:[1,0]
	v_cvt_pk_fp8_f32 v110, v112, v113 op_sel:[0,0,1]
	v_pk_fma_f32 v[106:107], v[42:43], v[106:107], v[46:47]
	v_pk_mul_f32 v[112:113], v[122:123], v[164:165] op_sel_hi:[1,0]
	v_pk_mul_f32 v[122:123], v[124:125], v[164:165] op_sel_hi:[1,0]
	v_pk_fma_f32 v[112:113], v[34:35], v[112:113], v[38:39]
	v_med3_f32 v124, v106, s20, v156
	v_med3_f32 v107, v107, s20, v156
	v_mov_b32_e32 v106, 0
	v_cvt_pk_fp8_f32 v106, v124, v107
	v_med3_f32 v112, v112, s20, v156
	v_med3_f32 v113, v113, s20, v156
	v_mov_b32_e32 v107, 0
	v_pk_mul_f32 v[108:109], v[128:129], v[164:165] op_sel_hi:[1,0]
	v_cvt_pk_fp8_f32 v107, v112, v113
	v_pk_fma_f32 v[108:109], v[44:45], v[108:109], v[48:49]
	v_pk_fma_f32 v[122:123], v[36:37], v[122:123], v[40:41]
	v_med3_f32 v108, v108, s20, v156
	v_med3_f32 v109, v109, s20, v156
	v_cvt_pk_fp8_f32 v106, v108, v109 op_sel:[0,0,1]
	v_med3_f32 v108, v122, s20, v156
	v_med3_f32 v109, v123, s20, v156
	v_cvt_pk_fp8_f32 v107, v108, v109 op_sel:[0,0,1]
	v_lshl_add_u64 v[108:109], s[0:1], 0, v[130:131]
	ds_read_b128 v[10:13], v6 offset:6144
	ds_read_b128 v[2:5], v6 offset:6160
	ds_read_b128 v[14:17], v6 offset:14336
	ds_read_b128 v[6:9], v6 offset:14352
	global_store_dwordx2 v[108:109], v[110:111], off
	v_lshl_add_u64 v[108:109], s[0:1], 0, v[136:137]
	global_store_dwordx2 v[108:109], v[106:107], off
	v_pk_mul_f32 v[106:107], v[118:119], v[164:165] op_sel_hi:[1,0]
	v_pk_mul_f32 v[110:111], v[114:115], v[164:165] op_sel_hi:[1,0]
	v_pk_fma_f32 v[106:107], v[26:27], v[106:107], v[30:31]
	v_pk_fma_f32 v[110:111], v[18:19], v[110:111], v[22:23]
	v_med3_f32 v114, v106, s20, v156
	v_med3_f32 v107, v107, s20, v156
	v_mov_b32_e32 v106, 0
	v_cvt_pk_fp8_f32 v106, v114, v107
	v_med3_f32 v110, v110, s20, v156
	v_med3_f32 v111, v111, s20, v156
	v_mov_b32_e32 v107, 0
	v_pk_mul_f32 v[108:109], v[120:121], v[164:165] op_sel_hi:[1,0]
	v_cvt_pk_fp8_f32 v107, v110, v111
	v_pk_fma_f32 v[108:109], v[28:29], v[108:109], v[32:33]
	v_pk_mul_f32 v[112:113], v[116:117], v[164:165] op_sel_hi:[1,0]
	v_med3_f32 v108, v108, s20, v156
	v_pk_fma_f32 v[112:113], v[20:21], v[112:113], v[24:25]
	v_med3_f32 v109, v109, s20, v156
	v_pk_mul_f32 v[102:103], v[102:103], v[164:165] op_sel_hi:[1,0]
	v_cvt_pk_fp8_f32 v106, v108, v109 op_sel:[0,0,1]
	v_med3_f32 v108, v112, s20, v156
	v_med3_f32 v109, v113, s20, v156
	s_waitcnt lgkmcnt(1)
; #define GAS __attribute__((address_space(1)))
; __device__ __forceinline__ unsigned pk2(float lo, float hi) { return f2bf(lo) | (f2bf(hi) << 16); }
; #define NPR_LOAD(slot, row) do { _Pragma("unroll") for (int j = 0; j < 4; ++j) { const size_t o = (size_t)(row) * DM + 8 * (flane + 64 * j); \
;             if (P16) raw[P16 ? (slot) : 0][j] = *(const v4u*)(X16 + o); \
;             else { vf[P16 ? 0 : (slot)][j][0] = *(const f32x4*)(srcP32 + o); vf[P16 ? 0 : (slot)][j][1] = *(const f32x4*)(srcP32 + o + 4); } } } while (0)
; template <int OUTM, bool P16>
; __device__ __forceinline__ void norm_prompt_rows(Frame& F, const float* srcP32, const float* gain, int sub, bf16* Hd, float* yP) {
;     ...
;         for (int r = 0; r < 4; ++r) {
;             const int slot = r % RB;
;             float ss = 0.f;
; #pragma unroll
;             for (int j = 0; j < 4; ++j) { f32x4 x0, x1; NPR_GET(slot, j, x0, x1);
;                 ss += ((x0[0] * x0[0] + x0[1] * x0[1]) + (x0[2] * x0[2] + x0[3] * x0[3])) + ((x1[0] * x1[0] + x1[1] * x1[1]) + (x1[2] * x1[2] + x1[3] * x1[3])); }
;             const float rstd = 1.0f / sqrtf(wave_sum(ss) * (1.0f / DM) + EPS);
;     ...
;             for (int j = 0; j < 4; ++j) { const size_t o = (size_t)(m0 + r) * DM + 8 * (flane + 64 * j);
;                 f32x4 x0, x1; NPR_GET(slot, j, x0, x1);
;                 const f32x4 o0 = (x0 * rstd) * Am[j][0] + Bm[j][0], o1 = (x1 * rstd) * Am[j][1] + Bm[j][1];
;                 if (OUTM == 2) { __builtin_nontemporal_store(o0, (f32x4*)(yP + o)); __builtin_nontemporal_store(o1, (f32x4*)(yP + o + 4)); }
;                 else if (OUTM == 1) { v2u pk; pk.x = pg8::pk4_fp8(o0[0], o0[1], o0[2], o0[3]); pk.y = pg8::pk4_fp8(o1[0], o1[1], o1[2], o1[3]); *(GAS v2u*)((unsigned char*)Hd + o) = pk; }
;                 else { v4u pk; pk.x = pk2(o0[0], o0[1]); pk.y = pk2(o0[2], o0[3]); pk.z = pk2(o1[0], o1[1]); pk.w = pk2(o1[2], o1[3]); *(GAS v4u*)(Hd + o) = pk; } }
;             if (r + RB < 4) NPR_LOAD(slot, m0 + r + RB);
	v_pk_fma_f32 v[102:103], v[10:11], v[102:103], v[14:15]
	v_pk_mul_f32 v[98:99], v[98:99], v[164:165] op_sel_hi:[1,0]
	v_cvt_pk_fp8_f32 v107, v108, v109 op_sel:[0,0,1]
	s_waitcnt lgkmcnt(0)
	v_pk_fma_f32 v[98:99], v[2:3], v[98:99], v[6:7]
	v_med3_f32 v108, v102, s20, v156
	v_med3_f32 v103, v103, s20, v156
	v_mov_b32_e32 v102, 0
	v_cvt_pk_fp8_f32 v102, v108, v103
	v_med3_f32 v98, v98, s20, v156
	v_med3_f32 v99, v99, s20, v156
	v_mov_b32_e32 v103, 0
	v_cvt_pk_fp8_f32 v103, v98, v99
	v_pk_mul_f32 v[104:105], v[104:105], v[164:165] op_sel_hi:[1,0]
	v_pk_mul_f32 v[100:101], v[100:101], v[164:165] op_sel_hi:[1,0]
	v_pk_fma_f32 v[104:105], v[12:13], v[104:105], v[16:17]
	v_pk_fma_f32 v[100:101], v[4:5], v[100:101], v[8:9]
	v_med3_f32 v104, v104, s20, v156
	v_med3_f32 v105, v105, s20, v156
	v_med3_f32 v98, v100, s20, v156
	v_med3_f32 v99, v101, s20, v156
	s_add_i32 s8, s2, 2
	v_cvt_pk_fp8_f32 v102, v104, v105 op_sel:[0,0,1]
	v_cvt_pk_fp8_f32 v103, v98, v99 op_sel:[0,0,1]
	v_lshl_add_u64 v[98:99], s[0:1], 0, v[134:135]
	s_ashr_i32 s9, s8, 31
	global_store_dwordx2 v[98:99], v[106:107], off
	v_lshl_add_u64 v[98:99], s[0:1], 0, v[132:133]
	s_lshl_b64 s[0:1], s[8:9], 13
	s_add_u32 s0, s80, s0
	s_addc_u32 s1, s81, s1
	global_store_dwordx2 v[98:99], v[102:103], off
	v_lshl_add_u64 v[98:99], s[0:1], 0, v[138:139]
	global_load_dwordx4 v[122:125], v[98:99], off offset:16 nt
	global_load_dwordx4 v[126:129], v[98:99], off nt
	v_lshl_add_u64 v[98:99], s[0:1], 0, v[140:141]
	global_load_dwordx4 v[114:117], v[98:99], off offset:16 nt
	global_load_dwordx4 v[118:121], v[98:99], off nt
	v_lshl_add_u64 v[98:99], s[0:1], 0, v[144:145]
	v_lshl_add_u64 v[102:103], s[0:1], 0, v[142:143]
	global_load_dwordx4 v[106:109], v[98:99], off offset:16 nt
	global_load_dwordx4 v[110:113], v[98:99], off nt
	s_nop 0
	global_load_dwordx4 v[98:101], v[102:103], off offset:16 nt
	s_nop 0
	global_load_dwordx4 v[102:105], v[102:103], off nt
	s_waitcnt vmcnt(18)
	v_pk_mul_f32 v[164:165], v[96:97], v[96:97]
	v_pk_mul_f32 v[166:167], v[94:95], v[94:95]
	s_waitcnt vmcnt(12)
	v_mul_f32_e32 v163, v70, v70
	v_pk_mov_b32 v[168:169], v[166:167], v[164:165] op_sel:[1,0]
	v_mov_b32_e32 v167, v165
	v_pk_add_f32 v[164:165], v[168:169], v[166:167]
	v_pk_mul_f32 v[166:167], v[92:93], v[92:93]
	v_pk_mul_f32 v[168:169], v[90:91], v[90:91]
	v_pk_add_f32 v[164:165], v[164:165], v[164:165] op_sel:[0,1] op_sel_hi:[1,0]
	v_pk_mov_b32 v[170:171], v[168:169], v[166:167] op_sel:[1,0]
	v_mov_b32_e32 v169, v167
	v_pk_add_f32 v[166:167], v[170:171], v[168:169]
	v_pk_mul_f32 v[168:169], v[88:89], v[88:89]
	v_pk_mul_f32 v[170:171], v[86:87], v[86:87]
	v_pk_add_f32 v[166:167], v[166:167], v[166:167] op_sel:[0,1] op_sel_hi:[1,0]
	v_pk_mov_b32 v[172:173], v[170:171], v[168:169] op_sel:[1,0]
	v_mov_b32_e32 v171, v169
	v_pk_add_f32 v[168:169], v[172:173], v[170:171]
	v_pk_mul_f32 v[170:171], v[84:85], v[84:85]
	v_pk_mul_f32 v[172:173], v[82:83], v[82:83]
	v_mov_b32_e32 v165, v163
	v_pk_mov_b32 v[174:175], v[172:173], v[170:171] op_sel:[1,0]
	v_mov_b32_e32 v173, v171
	v_pk_add_f32 v[170:171], v[174:175], v[172:173]
	v_mul_f32_e32 v172, v71, v71
	v_mov_b32_e32 v167, v172
	v_mul_f32_e32 v173, v72, v72
	v_mul_f32_e32 v174, v73, v73
	v_pk_add_f32 v[164:165], v[164:165], v[166:167]
	v_pk_add_f32 v[166:167], v[168:169], v[168:169] op_sel:[0,1] op_sel_hi:[1,0]
	v_pk_add_f32 v[168:169], v[170:171], v[170:171] op_sel:[0,1] op_sel_hi:[1,0]
	v_mov_b32_e32 v167, v173
	v_mov_b32_e32 v169, v174
	v_pk_add_f32 v[166:167], v[166:167], v[168:169]
	v_mul_f32_e32 v168, v81, v81
	v_pk_add_f32 v[164:165], v[164:165], v[166:167]
	v_mul_f32_e32 v166, v79, v79
	v_mul_f32_e32 v175, v66, v66
	v_mul_f32_e32 v176, v67, v67
	v_pk_fma_f32 v[166:167], v[78:79], v[78:79], v[166:167] op_sel_hi:[1,1,0]
	v_pk_fma_f32 v[168:169], v[80:81], v[80:81], v[168:169] op_sel_hi:[1,1,0]
	v_mov_b32_e32 v167, v175
	v_mov_b32_e32 v169, v176
	v_pk_add_f32 v[166:167], v[166:167], v[168:169]
	v_mul_f32_e32 v168, v75, v75
	v_mul_f32_e32 v170, v77, v77
	v_mul_f32_e32 v177, v68, v68
	v_mul_f32_e32 v178, v69, v69
	v_pk_fma_f32 v[168:169], v[74:75], v[74:75], v[168:169] op_sel_hi:[1,1,0]
	v_pk_fma_f32 v[170:171], v[76:77], v[76:77], v[170:171] op_sel_hi:[1,1,0]
	v_mov_b32_e32 v169, v177
	v_mov_b32_e32 v171, v178
	v_pk_add_f32 v[168:169], v[168:169], v[170:171]
	s_nop 0
	v_pk_add_f32 v[166:167], v[166:167], v[168:169]
	s_nop 0
	v_pk_add_f32 v[164:165], v[164:165], v[166:167]
	s_nop 0
	v_add_f32_e32 v163, v164, v165
	ds_bpermute_b32 v164, v157, v163
	s_waitcnt lgkmcnt(0)
	v_add_f32_e32 v163, v163, v164
	ds_bpermute_b32 v164, v158, v163
	s_waitcnt lgkmcnt(0)
	v_add_f32_e32 v163, v163, v164
	ds_bpermute_b32 v164, v159, v163
	s_waitcnt lgkmcnt(0)
	v_add_f32_e32 v163, v163, v164
	ds_bpermute_b32 v164, v160, v163
	s_waitcnt lgkmcnt(0)
	v_add_f32_e32 v163, v163, v164
	ds_bpermute_b32 v164, v161, v163
	s_waitcnt lgkmcnt(0)
	v_add_f32_e32 v163, v163, v164
	ds_bpermute_b32 v164, v162, v163
	s_waitcnt lgkmcnt(0)
; #define GAS __attribute__((address_space(1)))
; __device__ __forceinline__ unsigned pk2(float lo, float hi) { return f2bf(lo) | (f2bf(hi) << 16); }
; #define NPR_LOAD(slot, row) do { _Pragma("unroll") for (int j = 0; j < 4; ++j) { const size_t o = (size_t)(row) * DM + 8 * (flane + 64 * j); \
;             if (P16) raw[P16 ? (slot) : 0][j] = *(const v4u*)(X16 + o); \
;             else { vf[P16 ? 0 : (slot)][j][0] = *(const f32x4*)(srcP32 + o); vf[P16 ? 0 : (slot)][j][1] = *(const f32x4*)(srcP32 + o + 4); } } } while (0)
; template <int OUTM, bool P16>
; __device__ __forceinline__ void norm_prompt_rows(Frame& F, const float* srcP32, const float* gain, int sub, bf16* Hd, float* yP) {
;     ...
;             const float rstd = 1.0f / sqrtf(wave_sum(ss) * (1.0f / DM) + EPS);
; #pragma unroll
;             for (int j = 0; j < 4; ++j) { const size_t o = (size_t)(m0 + r) * DM + 8 * (flane + 64 * j);
;                 f32x4 x0, x1; NPR_GET(slot, j, x0, x1);
;                 const f32x4 o0 = (x0 * rstd) * Am[j][0] + Bm[j][0], o1 = (x1 * rstd) * Am[j][1] + Bm[j][1];
;                 if (OUTM == 2) { __builtin_nontemporal_store(o0, (f32x4*)(yP + o)); __builtin_nontemporal_store(o1, (f32x4*)(yP + o + 4)); }
;                 else if (OUTM == 1) { v2u pk; pk.x = pg8::pk4_fp8(o0[0], o0[1], o0[2], o0[3]); pk.y = pg8::pk4_fp8(o1[0], o1[1], o1[2], o1[3]); *(GAS v2u*)((unsigned char*)Hd + o) = pk; }
;                 else { v4u pk; pk.x = pk2(o0[0], o0[1]); pk.y = pk2(o0[2], o0[3]); pk.z = pk2(o1[0], o1[1]); pk.w = pk2(o1[2], o1[3]); *(GAS v4u*)(Hd + o) = pk; } }
;             if (r + RB < 4) NPR_LOAD(slot, m0 + r + RB);
	v_add_f32_e32 v163, v163, v164
	v_fmamk_f32 v163, v163, 0x3a000000, v154
	v_mul_f32_e32 v164, 0x4f800000, v163
	v_cmp_gt_f32_e32 vcc, s19, v163
	s_nop 1
	v_cndmask_b32_e32 v163, v163, v164, vcc
	v_sqrt_f32_e32 v164, v163
	s_nop 0
	v_add_u32_e32 v165, -1, v164
	v_fma_f32 v166, -v165, v164, v163
	v_cmp_ge_f32_e64 s[0:1], 0, v166
	v_add_u32_e32 v166, 1, v164
	s_nop 0
	v_cndmask_b32_e64 v165, v164, v165, s[0:1]
	v_fma_f32 v164, -v166, v164, v163
	v_cmp_lt_f32_e64 s[0:1], 0, v164
	s_nop 1
	v_cndmask_b32_e64 v164, v165, v166, s[0:1]
	v_mul_f32_e32 v165, 0x37800000, v164
	v_cndmask_b32_e32 v164, v164, v165, vcc
	v_cmp_class_f32_e32 vcc, v163, v155
	s_nop 1
	v_cndmask_b32_e32 v163, v164, v163, vcc
	v_div_scale_f32 v164, s[0:1], v163, v163, 1.0
	v_rcp_f32_e32 v165, v164
	s_lshl_b64 s[0:1], s[6:7], 11
	s_add_u32 s0, s4, s0
	s_addc_u32 s1, s5, s1
	v_fma_f32 v166, -v164, v165, 1.0
	v_fmac_f32_e32 v165, v166, v165
	v_div_scale_f32 v166, vcc, 1.0, v163, 1.0
	v_mul_f32_e32 v167, v166, v165
	v_fma_f32 v168, -v164, v167, v166
	v_fmac_f32_e32 v167, v168, v165
	v_fma_f32 v164, -v164, v167, v166
	v_div_fmas_f32 v164, v164, v165, v167
	v_div_fixup_f32 v164, v164, v163, 1.0
	v_pk_mul_f32 v[94:95], v[94:95], v[164:165] op_sel_hi:[1,0]
	v_pk_mul_f32 v[90:91], v[90:91], v[164:165] op_sel_hi:[1,0]
	v_pk_fma_f32 v[94:95], v[54:55], v[94:95], v[62:63]
	v_pk_fma_f32 v[90:91], v[50:51], v[90:91], v[58:59]
	v_med3_f32 v163, v94, s20, v156
	v_med3_f32 v95, v95, s20, v156
	v_mov_b32_e32 v94, 0
	v_cvt_pk_fp8_f32 v94, v163, v95
	v_med3_f32 v90, v90, s20, v156
	v_med3_f32 v91, v91, s20, v156
	v_mov_b32_e32 v95, 0
	v_cvt_pk_fp8_f32 v95, v90, v91
	v_pk_mul_f32 v[92:93], v[92:93], v[164:165] op_sel_hi:[1,0]
	v_pk_mul_f32 v[86:87], v[86:87], v[164:165] op_sel_hi:[1,0]
	v_pk_fma_f32 v[92:93], v[52:53], v[92:93], v[60:61]
	v_pk_fma_f32 v[86:87], v[42:43], v[86:87], v[46:47]
	v_med3_f32 v90, v92, s20, v156
	v_med3_f32 v91, v93, s20, v156
	v_pk_mul_f32 v[82:83], v[82:83], v[164:165] op_sel_hi:[1,0]
	v_cvt_pk_fp8_f32 v95, v90, v91 op_sel:[0,0,1]
	v_pk_fma_f32 v[82:83], v[34:35], v[82:83], v[38:39]
	v_med3_f32 v90, v86, s20, v156
	v_med3_f32 v87, v87, s20, v156
	v_mov_b32_e32 v86, 0
	v_cvt_pk_fp8_f32 v86, v90, v87
	v_med3_f32 v82, v82, s20, v156
	v_med3_f32 v83, v83, s20, v156
	v_mov_b32_e32 v87, 0
	v_pk_mul_f32 v[96:97], v[96:97], v[164:165] op_sel_hi:[1,0]
	v_cvt_pk_fp8_f32 v87, v82, v83
	v_pk_fma_f32 v[96:97], v[56:57], v[96:97], v[64:65]
	v_pk_mul_f32 v[88:89], v[88:89], v[164:165] op_sel_hi:[1,0]
	v_pk_mul_f32 v[84:85], v[84:85], v[164:165] op_sel_hi:[1,0]
	v_med3_f32 v96, v96, s20, v156
	v_med3_f32 v97, v97, s20, v156
	v_pk_fma_f32 v[88:89], v[44:45], v[88:89], v[48:49]
	v_pk_fma_f32 v[84:85], v[36:37], v[84:85], v[40:41]
	v_cvt_pk_fp8_f32 v94, v96, v97 op_sel:[0,0,1]
	v_med3_f32 v88, v88, s20, v156
	v_med3_f32 v89, v89, s20, v156
	v_med3_f32 v82, v84, s20, v156
	v_med3_f32 v83, v85, s20, v156
	v_cvt_pk_fp8_f32 v86, v88, v89 op_sel:[0,0,1]
	v_cvt_pk_fp8_f32 v87, v82, v83 op_sel:[0,0,1]
	v_lshl_add_u64 v[82:83], s[0:1], 0, v[130:131]
	v_pk_mul_f32 v[78:79], v[78:79], v[164:165] op_sel_hi:[1,0]
	global_store_dwordx2 v[82:83], v[94:95], off
	v_lshl_add_u64 v[82:83], s[0:1], 0, v[136:137]
	v_pk_fma_f32 v[78:79], v[26:27], v[78:79], v[30:31]
	v_pk_mul_f32 v[74:75], v[74:75], v[164:165] op_sel_hi:[1,0]
	global_store_dwordx2 v[82:83], v[86:87], off
	v_pk_fma_f32 v[74:75], v[18:19], v[74:75], v[22:23]
	v_med3_f32 v82, v78, s20, v156
	v_med3_f32 v79, v79, s20, v156
	v_mov_b32_e32 v78, 0
	v_cvt_pk_fp8_f32 v78, v82, v79
	v_med3_f32 v74, v74, s20, v156
	v_med3_f32 v75, v75, s20, v156
	v_mov_b32_e32 v79, 0
	v_cvt_pk_fp8_f32 v79, v74, v75
	v_pk_mul_f32 v[76:77], v[76:77], v[164:165] op_sel_hi:[1,0]
	v_pk_mul_f32 v[70:71], v[70:71], v[164:165] op_sel_hi:[1,0]
	v_pk_fma_f32 v[76:77], v[20:21], v[76:77], v[24:25]
	v_pk_fma_f32 v[70:71], v[10:11], v[70:71], v[14:15]
	v_med3_f32 v74, v76, s20, v156
	v_med3_f32 v75, v77, s20, v156
	v_pk_mul_f32 v[66:67], v[66:67], v[164:165] op_sel_hi:[1,0]
	v_pk_mul_f32 v[80:81], v[80:81], v[164:165] op_sel_hi:[1,0]
	v_cvt_pk_fp8_f32 v79, v74, v75 op_sel:[0,0,1]
	v_pk_fma_f32 v[66:67], v[2:3], v[66:67], v[6:7]
	v_med3_f32 v74, v70, s20, v156
	v_med3_f32 v71, v71, s20, v156
	v_mov_b32_e32 v70, 0
	v_pk_fma_f32 v[80:81], v[28:29], v[80:81], v[32:33]
	v_cvt_pk_fp8_f32 v70, v74, v71
	v_med3_f32 v66, v66, s20, v156
	v_med3_f32 v67, v67, s20, v156
	v_mov_b32_e32 v71, 0
	v_med3_f32 v80, v80, s20, v156
	v_med3_f32 v81, v81, s20, v156
	v_cvt_pk_fp8_f32 v71, v66, v67
	v_cvt_pk_fp8_f32 v78, v80, v81 op_sel:[0,0,1]
	v_pk_mul_f32 v[72:73], v[72:73], v[164:165] op_sel_hi:[1,0]
	v_pk_mul_f32 v[68:69], v[68:69], v[164:165] op_sel_hi:[1,0]
	v_pk_fma_f32 v[72:73], v[12:13], v[72:73], v[16:17]
	v_pk_fma_f32 v[68:69], v[4:5], v[68:69], v[8:9]
	v_med3_f32 v72, v72, s20, v156
	v_med3_f32 v73, v73, s20, v156
	v_med3_f32 v66, v68, s20, v156
	v_med3_f32 v67, v69, s20, v156
	s_add_i32 s2, s2, 3
	v_cvt_pk_fp8_f32 v70, v72, v73 op_sel:[0,0,1]
	v_cvt_pk_fp8_f32 v71, v66, v67 op_sel:[0,0,1]
	v_lshl_add_u64 v[66:67], s[0:1], 0, v[134:135]
	s_ashr_i32 s3, s2, 31
	global_store_dwordx2 v[66:67], v[78:79], off
	v_lshl_add_u64 v[66:67], s[0:1], 0, v[132:133]
	s_lshl_b64 s[0:1], s[2:3], 13
	s_add_u32 s0, s80, s0
	s_addc_u32 s1, s81, s1
	global_store_dwordx2 v[66:67], v[70:71], off
	v_lshl_add_u64 v[66:67], s[0:1], 0, v[138:139]
	global_load_dwordx4 v[90:93], v[66:67], off offset:16 nt
	global_load_dwordx4 v[94:97], v[66:67], off nt
	v_lshl_add_u64 v[66:67], s[0:1], 0, v[140:141]
	global_load_dwordx4 v[82:85], v[66:67], off offset:16 nt
	global_load_dwordx4 v[86:89], v[66:67], off nt
	v_lshl_add_u64 v[66:67], s[0:1], 0, v[144:145]
	v_lshl_add_u64 v[70:71], s[0:1], 0, v[142:143]
	global_load_dwordx4 v[74:77], v[66:67], off offset:16 nt
	global_load_dwordx4 v[78:81], v[66:67], off nt
	s_nop 0
	global_load_dwordx4 v[66:69], v[70:71], off offset:16 nt
	s_nop 0
	global_load_dwordx4 v[70:73], v[70:71], off nt
	s_waitcnt vmcnt(18)
; template <int OUTM, bool P16>
; __device__ __forceinline__ void norm_prompt_rows(Frame& F, const float* srcP32, const float* gain, int sub, bf16* Hd, float* yP) {
;     ...
;         for (int r = 0; r < 4; ++r) {
;             const int slot = r % RB;
;             float ss = 0.f;
; #pragma unroll
;             for (int j = 0; j < 4; ++j) { f32x4 x0, x1; NPR_GET(slot, j, x0, x1);
;                 ss += ((x0[0] * x0[0] + x0[1] * x0[1]) + (x0[2] * x0[2] + x0[3] * x0[3])) + ((x1[0] * x1[0] + x1[1] * x1[1]) + (x1[2] * x1[2] + x1[3] * x1[3])); }
;             const float rstd = 1.0f / sqrtf(wave_sum(ss) * (1.0f / DM) + EPS);
; #pragma unroll
;             for (int j = 0; j < 4; ++j) { const size_t o = (size_t)(m0 + r) * DM + 8 * (flane + 64 * j);
;                 f32x4 x0, x1; NPR_GET(slot, j, x0, x1);
;                 const f32x4 o0 = (x0 * rstd) * Am[j][0] + Bm[j][0], o1 = (x1 * rstd) * Am[j][1] + Bm[j][1];
	v_pk_mul_f32 v[138:139], v[128:129], v[128:129]
	v_pk_mul_f32 v[140:141], v[126:127], v[126:127]
	s_waitcnt vmcnt(12)
	v_mul_f32_e32 v163, v102, v102
	v_pk_mov_b32 v[142:143], v[140:141], v[138:139] op_sel:[1,0]
	v_mov_b32_e32 v141, v139
	v_pk_add_f32 v[138:139], v[142:143], v[140:141]
	v_pk_mul_f32 v[140:141], v[124:125], v[124:125]
	v_pk_mul_f32 v[142:143], v[122:123], v[122:123]
	v_pk_add_f32 v[138:139], v[138:139], v[138:139] op_sel:[0,1] op_sel_hi:[1,0]
	v_pk_mov_b32 v[144:145], v[142:143], v[140:141] op_sel:[1,0]
	v_mov_b32_e32 v143, v141
	v_pk_add_f32 v[140:141], v[144:145], v[142:143]
	v_pk_mul_f32 v[142:143], v[120:121], v[120:121]
	v_pk_mul_f32 v[144:145], v[118:119], v[118:119]
	v_pk_add_f32 v[140:141], v[140:141], v[140:141] op_sel:[0,1] op_sel_hi:[1,0]
	v_pk_mov_b32 v[164:165], v[144:145], v[142:143] op_sel:[1,0]
	v_mov_b32_e32 v145, v143
	v_pk_add_f32 v[142:143], v[164:165], v[144:145]
	v_pk_mul_f32 v[144:145], v[116:117], v[116:117]
	v_pk_mul_f32 v[164:165], v[114:115], v[114:115]
	v_mov_b32_e32 v139, v163
	v_pk_mov_b32 v[166:167], v[164:165], v[144:145] op_sel:[1,0]
	v_mov_b32_e32 v165, v145
	v_pk_add_f32 v[144:145], v[166:167], v[164:165]
	v_mul_f32_e32 v164, v103, v103
	v_mov_b32_e32 v141, v164
	v_mul_f32_e32 v165, v104, v104
	v_mul_f32_e32 v166, v105, v105
	v_pk_add_f32 v[138:139], v[138:139], v[140:141]
	v_pk_add_f32 v[140:141], v[142:143], v[142:143] op_sel:[0,1] op_sel_hi:[1,0]
	v_pk_add_f32 v[142:143], v[144:145], v[144:145] op_sel:[0,1] op_sel_hi:[1,0]
	v_mov_b32_e32 v141, v165
	v_mov_b32_e32 v143, v166
	v_pk_add_f32 v[140:141], v[140:141], v[142:143]
	v_mul_f32_e32 v142, v113, v113
	v_pk_add_f32 v[138:139], v[138:139], v[140:141]
	v_mul_f32_e32 v140, v111, v111
	v_mul_f32_e32 v167, v98, v98
	v_mul_f32_e32 v168, v99, v99
	v_pk_fma_f32 v[140:141], v[110:111], v[110:111], v[140:141] op_sel_hi:[1,1,0]
	v_pk_fma_f32 v[142:143], v[112:113], v[112:113], v[142:143] op_sel_hi:[1,1,0]
	v_mov_b32_e32 v141, v167
	v_mov_b32_e32 v143, v168
	v_pk_add_f32 v[140:141], v[140:141], v[142:143]
	v_mul_f32_e32 v142, v107, v107
	v_mul_f32_e32 v144, v109, v109
	v_mul_f32_e32 v169, v100, v100
	v_mul_f32_e32 v170, v101, v101
	v_pk_fma_f32 v[142:143], v[106:107], v[106:107], v[142:143] op_sel_hi:[1,1,0]
	v_pk_fma_f32 v[144:145], v[108:109], v[108:109], v[144:145] op_sel_hi:[1,1,0]
	v_mov_b32_e32 v143, v169
	v_mov_b32_e32 v145, v170
	v_pk_add_f32 v[142:143], v[142:143], v[144:145]
	s_nop 0
	v_pk_add_f32 v[140:141], v[140:141], v[142:143]
	s_nop 0
	v_pk_add_f32 v[138:139], v[138:139], v[140:141]
	s_nop 0
	v_add_f32_e32 v138, v138, v139
	ds_bpermute_b32 v139, v157, v138
	s_waitcnt lgkmcnt(0)
	v_add_f32_e32 v138, v138, v139
	ds_bpermute_b32 v139, v158, v138
	s_waitcnt lgkmcnt(0)
	v_add_f32_e32 v138, v138, v139
	ds_bpermute_b32 v139, v159, v138
	s_waitcnt lgkmcnt(0)
	v_add_f32_e32 v138, v138, v139
	ds_bpermute_b32 v139, v160, v138
	s_waitcnt lgkmcnt(0)
	v_add_f32_e32 v138, v138, v139
	ds_bpermute_b32 v139, v161, v138
	s_waitcnt lgkmcnt(0)
	v_add_f32_e32 v138, v138, v139
	ds_bpermute_b32 v139, v162, v138
	s_waitcnt lgkmcnt(0)
	v_add_f32_e32 v138, v138, v139
	v_fmamk_f32 v138, v138, 0x3a000000, v154
	v_mul_f32_e32 v139, 0x4f800000, v138
	v_cmp_gt_f32_e32 vcc, s19, v138
	s_nop 1
	v_cndmask_b32_e32 v138, v138, v139, vcc
	v_sqrt_f32_e32 v139, v138
	s_nop 0
	v_add_u32_e32 v140, -1, v139
	v_fma_f32 v141, -v140, v139, v138
	v_cmp_ge_f32_e64 s[0:1], 0, v141
	v_add_u32_e32 v141, 1, v139
	s_nop 0
	v_cndmask_b32_e64 v140, v139, v140, s[0:1]
	v_fma_f32 v139, -v141, v139, v138
	v_cmp_lt_f32_e64 s[0:1], 0, v139
	s_nop 1
	v_cndmask_b32_e64 v139, v140, v141, s[0:1]
	v_mul_f32_e32 v140, 0x37800000, v139
	v_cndmask_b32_e32 v139, v139, v140, vcc
	v_cmp_class_f32_e32 vcc, v138, v155
	s_nop 1
	v_cndmask_b32_e32 v138, v139, v138, vcc
	v_div_scale_f32 v139, s[0:1], v138, v138, 1.0
	v_rcp_f32_e32 v140, v139
	s_lshl_b64 s[0:1], s[8:9], 11
	s_add_u32 s0, s4, s0
	s_addc_u32 s1, s5, s1
	v_fma_f32 v141, -v139, v140, 1.0
	v_fmac_f32_e32 v140, v141, v140
	v_div_scale_f32 v141, vcc, 1.0, v138, 1.0
	v_mul_f32_e32 v142, v141, v140
	v_fma_f32 v143, -v139, v142, v141
	v_fmac_f32_e32 v142, v143, v140
	v_fma_f32 v139, -v139, v142, v141
	v_div_fmas_f32 v139, v139, v140, v142
	v_div_fixup_f32 v138, v139, v138, 1.0
	v_pk_mul_f32 v[126:127], v[126:127], v[138:139] op_sel_hi:[1,0]
	v_pk_mul_f32 v[122:123], v[122:123], v[138:139] op_sel_hi:[1,0]
	v_pk_fma_f32 v[126:127], v[54:55], v[126:127], v[62:63]
	v_pk_mul_f32 v[128:129], v[128:129], v[138:139] op_sel_hi:[1,0]
	v_pk_mul_f32 v[124:125], v[124:125], v[138:139] op_sel_hi:[1,0]
	v_pk_fma_f32 v[122:123], v[50:51], v[122:123], v[58:59]
	v_med3_f32 v139, v126, s20, v156
	v_med3_f32 v127, v127, s20, v156
	v_mov_b32_e32 v126, 0
	v_cvt_pk_fp8_f32 v126, v139, v127
	v_med3_f32 v122, v122, s20, v156
	v_med3_f32 v123, v123, s20, v156
	v_mov_b32_e32 v127, 0
	v_cvt_pk_fp8_f32 v127, v122, v123
	v_pk_fma_f32 v[124:125], v[52:53], v[124:125], v[60:61]
	v_pk_mul_f32 v[118:119], v[118:119], v[138:139] op_sel_hi:[1,0]
	v_med3_f32 v122, v124, s20, v156
	v_med3_f32 v123, v125, s20, v156
	v_pk_fma_f32 v[118:119], v[42:43], v[118:119], v[46:47]
	v_pk_mul_f32 v[114:115], v[114:115], v[138:139] op_sel_hi:[1,0]
	v_cvt_pk_fp8_f32 v127, v122, v123 op_sel:[0,0,1]
	v_pk_fma_f32 v[114:115], v[34:35], v[114:115], v[38:39]
	v_med3_f32 v122, v118, s20, v156
	v_med3_f32 v119, v119, s20, v156
	v_mov_b32_e32 v118, 0
	v_cvt_pk_fp8_f32 v118, v122, v119
	v_med3_f32 v114, v114, s20, v156
	v_med3_f32 v115, v115, s20, v156
	v_mov_b32_e32 v119, 0
	v_cvt_pk_fp8_f32 v119, v114, v115
	v_pk_fma_f32 v[128:129], v[56:57], v[128:129], v[64:65]
	v_pk_mul_f32 v[120:121], v[120:121], v[138:139] op_sel_hi:[1,0]
; #define GAS __attribute__((address_space(1)))
; __device__ __forceinline__ unsigned pk2(float lo, float hi) { return f2bf(lo) | (f2bf(hi) << 16); }
; #define NPR_LOAD(slot, row) do { _Pragma("unroll") for (int j = 0; j < 4; ++j) { const size_t o = (size_t)(row) * DM + 8 * (flane + 64 * j); \
;             if (P16) raw[P16 ? (slot) : 0][j] = *(const v4u*)(X16 + o); \
;             else { vf[P16 ? 0 : (slot)][j][0] = *(const f32x4*)(srcP32 + o); vf[P16 ? 0 : (slot)][j][1] = *(const f32x4*)(srcP32 + o + 4); } } } while (0)
; template <int OUTM, bool P16>
; __device__ __forceinline__ void norm_prompt_rows(Frame& F, const float* srcP32, const float* gain, int sub, bf16* Hd, float* yP) {
;     ...
;         for (int r = 0; r < 4; ++r) {
;             const int slot = r % RB;
;             float ss = 0.f;
; #pragma unroll
;             for (int j = 0; j < 4; ++j) { f32x4 x0, x1; NPR_GET(slot, j, x0, x1);
;                 ss += ((x0[0] * x0[0] + x0[1] * x0[1]) + (x0[2] * x0[2] + x0[3] * x0[3])) + ((x1[0] * x1[0] + x1[1] * x1[1]) + (x1[2] * x1[2] + x1[3] * x1[3])); }
;             const float rstd = 1.0f / sqrtf(wave_sum(ss) * (1.0f / DM) + EPS);
;     ...
;             for (int j = 0; j < 4; ++j) { const size_t o = (size_t)(m0 + r) * DM + 8 * (flane + 64 * j);
;                 f32x4 x0, x1; NPR_GET(slot, j, x0, x1);
;                 const f32x4 o0 = (x0 * rstd) * Am[j][0] + Bm[j][0], o1 = (x1 * rstd) * Am[j][1] + Bm[j][1];
;                 if (OUTM == 2) { __builtin_nontemporal_store(o0, (f32x4*)(yP + o)); __builtin_nontemporal_store(o1, (f32x4*)(yP + o + 4)); }
;                 else if (OUTM == 1) { v2u pk; pk.x = pg8::pk4_fp8(o0[0], o0[1], o0[2], o0[3]); pk.y = pg8::pk4_fp8(o1[0], o1[1], o1[2], o1[3]); *(GAS v2u*)((unsigned char*)Hd + o) = pk; }
;                 else { v4u pk; pk.x = pk2(o0[0], o0[1]); pk.y = pk2(o0[2], o0[3]); pk.z = pk2(o1[0], o1[1]); pk.w = pk2(o1[2], o1[3]); *(GAS v4u*)(Hd + o) = pk; } }
;             if (r + RB < 4) NPR_LOAD(slot, m0 + r + RB);
	v_pk_mul_f32 v[116:117], v[116:117], v[138:139] op_sel_hi:[1,0]
	v_med3_f32 v128, v128, s20, v156
	v_med3_f32 v129, v129, s20, v156
	v_pk_fma_f32 v[120:121], v[44:45], v[120:121], v[48:49]
	v_pk_fma_f32 v[116:117], v[36:37], v[116:117], v[40:41]
	v_cvt_pk_fp8_f32 v126, v128, v129 op_sel:[0,0,1]
	v_med3_f32 v120, v120, s20, v156
	v_med3_f32 v121, v121, s20, v156
	v_med3_f32 v114, v116, s20, v156
	v_med3_f32 v115, v117, s20, v156
	v_cvt_pk_fp8_f32 v118, v120, v121 op_sel:[0,0,1]
	v_cvt_pk_fp8_f32 v119, v114, v115 op_sel:[0,0,1]
	v_lshl_add_u64 v[114:115], s[0:1], 0, v[130:131]
	v_pk_mul_f32 v[110:111], v[110:111], v[138:139] op_sel_hi:[1,0]
	global_store_dwordx2 v[114:115], v[126:127], off
	v_lshl_add_u64 v[114:115], s[0:1], 0, v[136:137]
	v_pk_fma_f32 v[110:111], v[26:27], v[110:111], v[30:31]
	v_pk_mul_f32 v[106:107], v[106:107], v[138:139] op_sel_hi:[1,0]
	global_store_dwordx2 v[114:115], v[118:119], off
	v_pk_fma_f32 v[106:107], v[18:19], v[106:107], v[22:23]
	v_med3_f32 v114, v110, s20, v156
	v_med3_f32 v111, v111, s20, v156
	v_mov_b32_e32 v110, 0
	v_cvt_pk_fp8_f32 v110, v114, v111
	v_med3_f32 v106, v106, s20, v156
	v_med3_f32 v107, v107, s20, v156
	v_mov_b32_e32 v111, 0
	v_cvt_pk_fp8_f32 v111, v106, v107
	v_pk_mul_f32 v[108:109], v[108:109], v[138:139] op_sel_hi:[1,0]
	v_pk_mul_f32 v[102:103], v[102:103], v[138:139] op_sel_hi:[1,0]
	v_pk_fma_f32 v[108:109], v[20:21], v[108:109], v[24:25]
	v_pk_fma_f32 v[102:103], v[10:11], v[102:103], v[14:15]
	v_med3_f32 v106, v108, s20, v156
	v_med3_f32 v107, v109, s20, v156
	v_pk_mul_f32 v[98:99], v[98:99], v[138:139] op_sel_hi:[1,0]
	v_cvt_pk_fp8_f32 v111, v106, v107 op_sel:[0,0,1]
	v_pk_fma_f32 v[98:99], v[2:3], v[98:99], v[6:7]
	v_med3_f32 v106, v102, s20, v156
	v_med3_f32 v103, v103, s20, v156
	v_mov_b32_e32 v102, 0
	v_cvt_pk_fp8_f32 v102, v106, v103
	v_med3_f32 v98, v98, s20, v156
	v_med3_f32 v99, v99, s20, v156
	v_mov_b32_e32 v103, 0
	v_pk_mul_f32 v[112:113], v[112:113], v[138:139] op_sel_hi:[1,0]
	v_cvt_pk_fp8_f32 v103, v98, v99
	v_pk_fma_f32 v[112:113], v[28:29], v[112:113], v[32:33]
	v_pk_mul_f32 v[104:105], v[104:105], v[138:139] op_sel_hi:[1,0]
	v_pk_mul_f32 v[100:101], v[100:101], v[138:139] op_sel_hi:[1,0]
	v_med3_f32 v112, v112, s20, v156
	v_med3_f32 v113, v113, s20, v156
	v_pk_fma_f32 v[104:105], v[12:13], v[104:105], v[16:17]
	v_pk_fma_f32 v[100:101], v[4:5], v[100:101], v[8:9]
	v_cvt_pk_fp8_f32 v110, v112, v113 op_sel:[0,0,1]
	v_med3_f32 v104, v104, s20, v156
	v_med3_f32 v105, v105, s20, v156
	v_med3_f32 v98, v100, s20, v156
	v_med3_f32 v99, v101, s20, v156
	v_cvt_pk_fp8_f32 v102, v104, v105 op_sel:[0,0,1]
	v_cvt_pk_fp8_f32 v103, v98, v99 op_sel:[0,0,1]
	v_lshl_add_u64 v[98:99], s[0:1], 0, v[134:135]
	global_store_dwordx2 v[98:99], v[110:111], off
	v_lshl_add_u64 v[98:99], s[0:1], 0, v[132:133]
	global_store_dwordx2 v[98:99], v[102:103], off
	s_waitcnt vmcnt(10)
	v_pk_mul_f32 v[98:99], v[96:97], v[96:97]
	v_pk_mul_f32 v[100:101], v[94:95], v[94:95]
	s_waitcnt vmcnt(5)
	v_mul_f32_e32 v110, v66, v66
	v_pk_mov_b32 v[102:103], v[100:101], v[98:99] op_sel:[1,0]
	v_mov_b32_e32 v101, v99
	v_pk_add_f32 v[98:99], v[102:103], v[100:101]
	v_pk_mul_f32 v[100:101], v[92:93], v[92:93]
	v_pk_mul_f32 v[102:103], v[90:91], v[90:91]
	v_pk_add_f32 v[98:99], v[98:99], v[98:99] op_sel:[0,1] op_sel_hi:[1,0]
	v_pk_mov_b32 v[104:105], v[102:103], v[100:101] op_sel:[1,0]
	v_mov_b32_e32 v103, v101
	v_pk_add_f32 v[100:101], v[104:105], v[102:103]
	v_pk_mul_f32 v[102:103], v[88:89], v[88:89]
	v_pk_mul_f32 v[104:105], v[86:87], v[86:87]
	v_pk_add_f32 v[100:101], v[100:101], v[100:101] op_sel:[0,1] op_sel_hi:[1,0]
	v_pk_mov_b32 v[106:107], v[104:105], v[102:103] op_sel:[1,0]
	v_mov_b32_e32 v105, v103
	v_pk_add_f32 v[102:103], v[106:107], v[104:105]
	v_pk_mul_f32 v[104:105], v[84:85], v[84:85]
	v_pk_mul_f32 v[106:107], v[82:83], v[82:83]
	v_mul_f32_e32 v111, v67, v67
	v_pk_mov_b32 v[108:109], v[106:107], v[104:105] op_sel:[1,0]
	v_mov_b32_e32 v107, v105
	v_pk_add_f32 v[104:105], v[108:109], v[106:107]
	s_waitcnt vmcnt(4)
	v_mul_f32_e32 v106, v70, v70
	v_mul_f32_e32 v107, v71, v71
	v_mov_b32_e32 v99, v106
	v_mov_b32_e32 v101, v107
	v_mul_f32_e32 v108, v72, v72
	v_mul_f32_e32 v109, v73, v73
	v_pk_add_f32 v[98:99], v[98:99], v[100:101]
	v_pk_add_f32 v[100:101], v[102:103], v[102:103] op_sel:[0,1] op_sel_hi:[1,0]
	v_pk_add_f32 v[102:103], v[104:105], v[104:105] op_sel:[0,1] op_sel_hi:[1,0]
	v_mov_b32_e32 v101, v108
	v_mov_b32_e32 v103, v109
	v_pk_add_f32 v[100:101], v[100:101], v[102:103]
	v_mul_f32_e32 v102, v81, v81
	v_pk_add_f32 v[98:99], v[98:99], v[100:101]
	v_mul_f32_e32 v100, v79, v79
	v_pk_fma_f32 v[100:101], v[78:79], v[78:79], v[100:101] op_sel_hi:[1,1,0]
	v_pk_fma_f32 v[102:103], v[80:81], v[80:81], v[102:103] op_sel_hi:[1,1,0]
	v_mov_b32_e32 v101, v110
	v_mov_b32_e32 v103, v111
	v_pk_add_f32 v[100:101], v[100:101], v[102:103]
	v_mul_f32_e32 v102, v75, v75
	v_mul_f32_e32 v104, v77, v77
	v_mul_f32_e32 v112, v68, v68
	v_mul_f32_e32 v113, v69, v69
	v_pk_fma_f32 v[102:103], v[74:75], v[74:75], v[102:103] op_sel_hi:[1,1,0]
	v_pk_fma_f32 v[104:105], v[76:77], v[76:77], v[104:105] op_sel_hi:[1,1,0]
	v_mov_b32_e32 v103, v112
	v_mov_b32_e32 v105, v113
	v_pk_add_f32 v[102:103], v[102:103], v[104:105]
	s_nop 0
	v_pk_add_f32 v[100:101], v[100:101], v[102:103]
	s_nop 0
	v_pk_add_f32 v[98:99], v[98:99], v[100:101]
	s_nop 0
	v_add_f32_e32 v98, v98, v99
	ds_bpermute_b32 v99, v157, v98
	s_waitcnt lgkmcnt(0)
	v_add_f32_e32 v98, v98, v99
	ds_bpermute_b32 v99, v158, v98
	s_waitcnt lgkmcnt(0)
	v_add_f32_e32 v98, v98, v99
	ds_bpermute_b32 v99, v159, v98
	s_waitcnt lgkmcnt(0)
	v_add_f32_e32 v98, v98, v99
	ds_bpermute_b32 v99, v160, v98
	s_waitcnt lgkmcnt(0)
; #define GAS __attribute__((address_space(1)))
; __device__ __forceinline__ unsigned pk2(float lo, float hi) { return f2bf(lo) | (f2bf(hi) << 16); }
; #define NPR_LOAD(slot, row) do { _Pragma("unroll") for (int j = 0; j < 4; ++j) { const size_t o = (size_t)(row) * DM + 8 * (flane + 64 * j); \
;             if (P16) raw[P16 ? (slot) : 0][j] = *(const v4u*)(X16 + o); \
;             else { vf[P16 ? 0 : (slot)][j][0] = *(const f32x4*)(srcP32 + o); vf[P16 ? 0 : (slot)][j][1] = *(const f32x4*)(srcP32 + o + 4); } } } while (0)
; template <int OUTM, bool P16>
; __device__ __forceinline__ void norm_prompt_rows(Frame& F, const float* srcP32, const float* gain, int sub, bf16* Hd, float* yP) {
;     ...
;     for (int mb = 32 * F.vcu; mb < MP; mb += 32 * F.G) {
;     ...
;             const float rstd = 1.0f / sqrtf(wave_sum(ss) * (1.0f / DM) + EPS);
; #pragma unroll
;             for (int j = 0; j < 4; ++j) { const size_t o = (size_t)(m0 + r) * DM + 8 * (flane + 64 * j);
;                 f32x4 x0, x1; NPR_GET(slot, j, x0, x1);
;                 const f32x4 o0 = (x0 * rstd) * Am[j][0] + Bm[j][0], o1 = (x1 * rstd) * Am[j][1] + Bm[j][1];
;                 if (OUTM == 2) { __builtin_nontemporal_store(o0, (f32x4*)(yP + o)); __builtin_nontemporal_store(o1, (f32x4*)(yP + o + 4)); }
;                 else if (OUTM == 1) { v2u pk; pk.x = pg8::pk4_fp8(o0[0], o0[1], o0[2], o0[3]); pk.y = pg8::pk4_fp8(o1[0], o1[1], o1[2], o1[3]); *(GAS v2u*)((unsigned char*)Hd + o) = pk; }
;                 else { v4u pk; pk.x = pk2(o0[0], o0[1]); pk.y = pk2(o0[2], o0[3]); pk.z = pk2(o1[0], o1[1]); pk.w = pk2(o1[2], o1[3]); *(GAS v4u*)(Hd + o) = pk; } }
;             if (r + RB < 4) NPR_LOAD(slot, m0 + r + RB);
;             __builtin_amdgcn_sched_barrier(0);
;         }
;         if (OUTM != 2) __syncthreads();
;     }
	v_add_f32_e32 v98, v98, v99
	ds_bpermute_b32 v99, v161, v98
	s_waitcnt lgkmcnt(0)
	v_add_f32_e32 v98, v98, v99
	ds_bpermute_b32 v99, v162, v98
	s_waitcnt lgkmcnt(0)
	v_add_f32_e32 v98, v98, v99
	v_fmamk_f32 v98, v98, 0x3a000000, v154
	v_mul_f32_e32 v99, 0x4f800000, v98
	v_cmp_gt_f32_e32 vcc, s19, v98
	s_nop 1
	v_cndmask_b32_e32 v98, v98, v99, vcc
	v_sqrt_f32_e32 v99, v98
	s_nop 0
	v_add_u32_e32 v100, -1, v99
	v_fma_f32 v101, -v100, v99, v98
	v_cmp_ge_f32_e64 s[0:1], 0, v101
	v_add_u32_e32 v101, 1, v99
	s_nop 0
	v_cndmask_b32_e64 v100, v99, v100, s[0:1]
	v_fma_f32 v99, -v101, v99, v98
	v_cmp_lt_f32_e64 s[0:1], 0, v99
	s_nop 1
	v_cndmask_b32_e64 v99, v100, v101, s[0:1]
	v_mul_f32_e32 v100, 0x37800000, v99
	v_cndmask_b32_e32 v99, v99, v100, vcc
	v_cmp_class_f32_e32 vcc, v98, v155
	s_nop 1
	v_cndmask_b32_e32 v98, v99, v98, vcc
	v_div_scale_f32 v99, s[0:1], v98, v98, 1.0
	v_rcp_f32_e32 v100, v99
	s_lshl_b64 s[0:1], s[2:3], 11
	s_add_u32 s0, s4, s0
	s_addc_u32 s1, s5, s1
	v_fma_f32 v101, -v99, v100, 1.0
	v_fmac_f32_e32 v100, v101, v100
	v_div_scale_f32 v101, vcc, 1.0, v98, 1.0
	v_mul_f32_e32 v102, v101, v100
	v_fma_f32 v103, -v99, v102, v101
	v_fmac_f32_e32 v102, v103, v100
	v_fma_f32 v99, -v99, v102, v101
	v_div_fmas_f32 v99, v99, v100, v102
	v_div_fixup_f32 v98, v99, v98, 1.0
	v_pk_mul_f32 v[94:95], v[94:95], v[98:99] op_sel_hi:[1,0]
	v_pk_mul_f32 v[96:97], v[96:97], v[98:99] op_sel_hi:[1,0]
	v_pk_fma_f32 v[54:55], v[54:55], v[94:95], v[62:63]
	v_pk_mul_f32 v[62:63], v[90:91], v[98:99] op_sel_hi:[1,0]
	v_med3_f32 v55, v55, s20, v156
	v_pk_fma_f32 v[50:51], v[50:51], v[62:63], v[58:59]
	v_med3_f32 v58, v54, s20, v156
	v_mov_b32_e32 v54, 0
	v_cvt_pk_fp8_f32 v54, v58, v55
	v_med3_f32 v50, v50, s20, v156
	v_med3_f32 v51, v51, s20, v156
	v_mov_b32_e32 v55, 0
	v_cvt_pk_fp8_f32 v55, v50, v51
	v_pk_fma_f32 v[56:57], v[56:57], v[96:97], v[64:65]
	v_pk_mul_f32 v[64:65], v[92:93], v[98:99] op_sel_hi:[1,0]
	v_med3_f32 v56, v56, s20, v156
	v_pk_fma_f32 v[52:53], v[52:53], v[64:65], v[60:61]
	v_med3_f32 v57, v57, s20, v156
	v_med3_f32 v50, v52, s20, v156
	v_med3_f32 v51, v53, s20, v156
	v_cvt_pk_fp8_f32 v55, v50, v51 op_sel:[0,0,1]
	v_pk_mul_f32 v[50:51], v[86:87], v[98:99] op_sel_hi:[1,0]
	v_pk_mul_f32 v[52:53], v[88:89], v[98:99] op_sel_hi:[1,0]
	v_pk_fma_f32 v[42:43], v[42:43], v[50:51], v[46:47]
	v_pk_fma_f32 v[44:45], v[44:45], v[52:53], v[48:49]
	v_pk_mul_f32 v[46:47], v[82:83], v[98:99] op_sel_hi:[1,0]
	v_pk_mul_f32 v[48:49], v[84:85], v[98:99] op_sel_hi:[1,0]
	v_pk_fma_f32 v[34:35], v[34:35], v[46:47], v[38:39]
	v_pk_fma_f32 v[36:37], v[36:37], v[48:49], v[40:41]
	v_med3_f32 v39, v42, s20, v156
	v_med3_f32 v40, v43, s20, v156
	v_mov_b32_e32 v38, 0
	v_cvt_pk_fp8_f32 v38, v39, v40
	v_med3_f32 v34, v34, s20, v156
	v_med3_f32 v35, v35, s20, v156
	v_mov_b32_e32 v39, 0
	v_cvt_pk_fp8_f32 v39, v34, v35
	v_cvt_pk_fp8_f32 v54, v56, v57 op_sel:[0,0,1]
	v_med3_f32 v40, v44, s20, v156
	v_med3_f32 v41, v45, s20, v156
	v_med3_f32 v34, v36, s20, v156
	v_med3_f32 v35, v37, s20, v156
	v_cvt_pk_fp8_f32 v38, v40, v41 op_sel:[0,0,1]
	v_cvt_pk_fp8_f32 v39, v34, v35 op_sel:[0,0,1]
	v_lshl_add_u64 v[34:35], s[0:1], 0, v[130:131]
	global_store_dwordx2 v[34:35], v[54:55], off
	v_lshl_add_u64 v[34:35], s[0:1], 0, v[136:137]
	global_store_dwordx2 v[34:35], v[38:39], off
	v_pk_mul_f32 v[34:35], v[78:79], v[98:99] op_sel_hi:[1,0]
	v_pk_mul_f32 v[36:37], v[80:81], v[98:99] op_sel_hi:[1,0]
	v_pk_fma_f32 v[26:27], v[26:27], v[34:35], v[30:31]
	v_pk_fma_f32 v[28:29], v[28:29], v[36:37], v[32:33]
	v_pk_mul_f32 v[30:31], v[74:75], v[98:99] op_sel_hi:[1,0]
	v_pk_mul_f32 v[32:33], v[76:77], v[98:99] op_sel_hi:[1,0]
	v_pk_fma_f32 v[18:19], v[18:19], v[30:31], v[22:23]
	v_pk_fma_f32 v[20:21], v[20:21], v[32:33], v[24:25]
	v_med3_f32 v23, v26, s20, v156
	v_med3_f32 v24, v27, s20, v156
	v_mov_b32_e32 v22, 0
	v_cvt_pk_fp8_f32 v22, v23, v24
	v_med3_f32 v18, v18, s20, v156
	v_med3_f32 v19, v19, s20, v156
	v_mov_b32_e32 v23, 0
	v_cvt_pk_fp8_f32 v23, v18, v19
	v_med3_f32 v18, v20, s20, v156
	v_med3_f32 v19, v21, s20, v156
	v_pk_mul_f32 v[20:21], v[72:73], v[98:99] op_sel_hi:[1,0]
	v_cvt_pk_fp8_f32 v23, v18, v19 op_sel:[0,0,1]
	v_pk_mul_f32 v[18:19], v[70:71], v[98:99] op_sel_hi:[1,0]
	v_pk_fma_f32 v[12:13], v[12:13], v[20:21], v[16:17]
	v_pk_fma_f32 v[10:11], v[10:11], v[18:19], v[14:15]
	v_pk_mul_f32 v[14:15], v[66:67], v[98:99] op_sel_hi:[1,0]
	v_pk_mul_f32 v[16:17], v[68:69], v[98:99] op_sel_hi:[1,0]
	v_pk_fma_f32 v[2:3], v[2:3], v[14:15], v[6:7]
	v_pk_fma_f32 v[4:5], v[4:5], v[16:17], v[8:9]
	v_med3_f32 v7, v10, s20, v156
	v_med3_f32 v8, v11, s20, v156
	v_mov_b32_e32 v6, 0
	v_cvt_pk_fp8_f32 v6, v7, v8
	v_med3_f32 v2, v2, s20, v156
	v_med3_f32 v3, v3, s20, v156
	v_mov_b32_e32 v7, 0
	v_cvt_pk_fp8_f32 v7, v2, v3
	v_med3_f32 v24, v28, s20, v156
	v_med3_f32 v25, v29, s20, v156
	v_cvt_pk_fp8_f32 v22, v24, v25 op_sel:[0,0,1]
	v_med3_f32 v8, v12, s20, v156
	v_med3_f32 v9, v13, s20, v156
	v_med3_f32 v2, v4, s20, v156
	v_med3_f32 v3, v5, s20, v156
	v_cvt_pk_fp8_f32 v6, v8, v9 op_sel:[0,0,1]
	v_cvt_pk_fp8_f32 v7, v2, v3 op_sel:[0,0,1]
	v_lshl_add_u64 v[2:3], s[0:1], 0, v[134:135]
	global_store_dwordx2 v[2:3], v[22:23], off
	v_lshl_add_u64 v[2:3], s[0:1], 0, v[132:133]
	global_store_dwordx2 v[2:3], v[6:7], off
	s_add_i32 s10, s10, s12
	s_cmpk_lt_i32 s10, 0x2000
	s_barrier
	s_cbranch_scc1 .LBB0_261
	s_mov_b64 s[78:79], s[50:51]
	s_mov_b64 s[76:77], s[48:49]
	s_mov_b64 s[74:75], s[46:47]
	s_mov_b64 s[72:73], s[44:45]
	s_mov_b64 s[70:71], s[42:43]
	s_mov_b64 s[68:69], s[40:41]
	s_mov_b64 s[66:67], s[38:39]
	s_mov_b64 s[64:65], s[36:37]
	s_mov_b64 s[36:37], s[80:81]
	s_mov_b64 s[44:45], s[88:89]
	s_mov_b64 s[38:39], s[82:83]
	s_mov_b64 s[46:47], s[90:91]

; __device__ __forceinline__ unsigned cvt_pk_bf16(float lo, float hi) { unsigned r; asm volatile("v_cvt_pk_bf16_f32 %0, %1, %2" : "=v"(r) : "v"(lo), "v"(hi)); return r; }
;     __device__ __forceinline__ void operator()(const f32x4 (&acc)[2][2][4][2], const Unit& u, int wr, int wc, int fr, int fq) const {
;     ...
;         if (u.kp < 0) {
;             const float* gp = gate + (size_t)(u.pm >> 3) * NMOD + col0;
;             f32x4 gg[2][2];
; #pragma unroll
;             for (int bj = 0; bj < 2; ++bj)
; #pragma unroll
;                 for (int n = 0; n < 2; ++n) gg[bj][n] = (*(const f32x4*)(gp + bj * HALF + 4 * n) + *(const f32x4*)(gp + MODSB_DELTA + bj * HALF + 4 * n)) * coef;
; #pragma unroll
;             for (int ai = 0; ai < 2; ++ai)
; #pragma unroll
;                 for (int m = 0; m < 4; ++m) {
;                     const int row = row0 + ai * HALF + m * 16;
;                     bf16_t* xp = X + (size_t)row * DM + col0;
; #pragma unroll
;                     for (int bj = 0; bj < 2; ++bj) {
;                         f32x4 b0, b1;
;                         if (BASE16) { const u32x4 bv = *(const u32x4*)(xp + bj * HALF);
;                             b0 = (f32x4){__builtin_bit_cast(float, bv.x << 16), __builtin_bit_cast(float, bv.x & 0xffff0000u), __builtin_bit_cast(float, bv.y << 16), __builtin_bit_cast(float, bv.y & 0xffff0000u)};
;                             b1 = (f32x4){__builtin_bit_cast(float, bv.z << 16), __builtin_bit_cast(float, bv.z & 0xffff0000u), __builtin_bit_cast(float, bv.w << 16), __builtin_bit_cast(float, bv.w & 0xffff0000u)}; }
;                         else { const float* bp = base32 + (size_t)row * DM + col0 + bj * HALF; b0 = __builtin_nontemporal_load((const f32x4*)bp); b1 = __builtin_nontemporal_load((const f32x4*)(bp + 4)); }
;                         const f32x4 o0 = b0 + gg[bj][0] * acc[ai][bj][m][0], o1 = b1 + gg[bj][1] * acc[ai][bj][m][1];
;                         u32x4 w; w.x = cvt_pk_bf16(o0[0], o0[1]); w.y = cvt_pk_bf16(o0[2], o0[3]); w.z = cvt_pk_bf16(o1[0], o1[1]); w.w = cvt_pk_bf16(o1[2], o1[3]);
;                         *(u32x4*)(xp + bj * HALF) = w;
;                     }
;                     if (m & 1) asm volatile("" ::: "memory");
;                 }
.LBB0_1518:
	s_ashr_i32 s30, s77, 3
	s_mul_hi_i32 s31, s30, 0x12000
	s_mul_i32 s30, s30, 0x12000
	s_add_u32 s30, s10, s30
	s_addc_u32 s31, s11, s31
	v_ashrrev_i32_e32 v11, 31, v10
	v_lshl_add_u64 v[22:23], v[8:9], 2, s[30:31]
	v_lshlrev_b64 v[10:11], 12, v[10:11]
	v_lshl_add_u64 v[10:11], s[8:9], 0, v[10:11]
	v_lshlrev_b64 v[24:25], 1, v[8:9]
	v_add_co_u32_e32 v194, vcc, s65, v22
	v_lshl_add_u64 v[8:9], v[10:11], 0, v[24:25]
	s_nop 0
	v_addc_co_u32_e32 v195, vcc, 0, v23, vcc
	v_lshl_add_u64 v[30:31], v[22:23], 0, s[16:17]
	global_load_dwordx4 v[10:13], v[8:9], off
	global_load_dwordx4 v[14:17], v[22:23], off offset:16
	global_load_dwordx4 v[18:21], v[22:23], off
	global_load_dwordx4 v[26:29], v[194:195], off
	v_lshl_add_u64 v[198:199], v[22:23], 0, s[18:19]
	global_load_dwordx4 v[30:33], v[30:31], off offset:16
	s_nop 0
	global_load_dwordx4 v[174:177], v[22:23], off offset:528
	global_load_dwordx4 v[178:181], v[22:23], off offset:512
	s_nop 0
	global_load_dwordx4 v[194:197], v[194:195], off offset:512
	s_nop 0
	global_load_dwordx4 v[198:201], v[198:199], off offset:16
	v_ashrrev_i32_e32 v7, 31, v6
	v_lshlrev_b64 v[6:7], 12, v[6:7]
	v_lshl_add_u64 v[6:7], s[8:9], 0, v[6:7]
	v_ashrrev_i32_e32 v5, 31, v4
	v_lshlrev_b64 v[4:5], 12, v[4:5]
	v_lshl_add_u64 v[4:5], s[8:9], 0, v[4:5]
	v_ashrrev_i32_e32 v3, 31, v2
	v_lshlrev_b64 v[2:3], 12, v[2:3]
	v_lshl_add_u64 v[2:3], s[8:9], 0, v[2:3]
	s_waitcnt vmcnt(0)
	v_lshlrev_b32_e32 v22, 16, v10
	v_and_b32_e32 v23, 0xffff0000, v10
	v_lshlrev_b32_e32 v202, 16, v11
	v_and_b32_e32 v203, 0xffff0000, v11
	v_pk_add_f32 v[10:11], v[20:21], v[28:29]
	v_pk_add_f32 v[20:21], v[14:15], v[30:31]
	v_lshlrev_b32_e32 v204, 16, v12
	v_and_b32_e32 v205, 0xffff0000, v12
	v_lshlrev_b32_e32 v206, 16, v13
	v_and_b32_e32 v207, 0xffff0000, v13
	v_pk_add_f32 v[12:13], v[18:19], v[26:27]
	v_pk_add_f32 v[18:19], v[16:17], v[32:33]
	v_pk_mul_f32 v[16:17], v[10:11], 0.5 op_sel_hi:[1,0]
	v_pk_mul_f32 v[10:11], v[20:21], 0.5 op_sel_hi:[1,0]
	v_pk_mul_f32 v[14:15], v[12:13], 0.5 op_sel_hi:[1,0]
	v_pk_mul_f32 v[12:13], v[18:19], 0.5 op_sel_hi:[1,0]
	v_pk_fma_f32 v[28:29], v[154:155], v[10:11], v[204:205]
	v_pk_fma_f32 v[18:19], v[160:161], v[16:17], v[202:203]
	v_pk_fma_f32 v[20:21], v[158:159], v[14:15], v[22:23]
	v_pk_fma_f32 v[22:23], v[156:157], v[12:13], v[206:207]
	v_cvt_pk_bf16_f32 v26, v20, v21
	v_cvt_pk_bf16_f32 v27, v18, v19
	v_cvt_pk_bf16_f32 v28, v28, v29
	v_lshl_add_u64 v[154:155], v[6:7], 0, v[24:25]
	v_cvt_pk_bf16_f32 v29, v22, v23
	global_load_dwordx4 v[30:33], v[8:9], off offset:256
	v_pk_add_f32 v[6:7], v[180:181], v[196:197]
	v_pk_add_f32 v[18:19], v[178:179], v[194:195]
	v_pk_add_f32 v[156:157], v[176:177], v[200:201]
	v_pk_add_f32 v[158:159], v[174:175], v[198:199]
	v_pk_mul_f32 v[22:23], v[6:7], 0.5 op_sel_hi:[1,0]
	v_pk_mul_f32 v[20:21], v[18:19], 0.5 op_sel_hi:[1,0]
	v_pk_mul_f32 v[18:19], v[156:157], 0.5 op_sel_hi:[1,0]
	v_pk_mul_f32 v[6:7], v[158:159], 0.5 op_sel_hi:[1,0]
	global_store_dwordx4 v[8:9], v[26:29], off sc1
	s_waitcnt vmcnt(1)
	s_nop 0
	v_lshlrev_b32_e32 v26, 16, v30
	v_and_b32_e32 v27, 0xffff0000, v30
	v_lshlrev_b32_e32 v28, 16, v31
	v_and_b32_e32 v29, 0xffff0000, v31
	v_lshlrev_b32_e32 v30, 16, v32
	v_and_b32_e32 v31, 0xffff0000, v32
	v_lshlrev_b32_e32 v32, 16, v33
	v_and_b32_e32 v33, 0xffff0000, v33
	v_pk_fma_f32 v[28:29], v[148:149], v[22:23], v[28:29]
	v_pk_fma_f32 v[26:27], v[146:147], v[20:21], v[26:27]
	v_pk_fma_f32 v[32:33], v[144:145], v[18:19], v[32:33]
	v_pk_fma_f32 v[30:31], v[142:143], v[6:7], v[30:31]
	v_cvt_pk_bf16_f32 v26, v26, v27
	v_cvt_pk_bf16_f32 v27, v28, v29
	s_nop 0
	v_cvt_pk_bf16_f32 v28, v30, v31
	v_cvt_pk_bf16_f32 v29, v32, v33
	global_load_dwordx4 v[30:33], v[154:155], off
	s_nop 0
	global_store_dwordx4 v[8:9], v[26:29], off offset:256 sc1
	s_waitcnt vmcnt(1)
	s_nop 0
	v_lshlrev_b32_e32 v26, 16, v30
	v_and_b32_e32 v27, 0xffff0000, v30
	v_lshlrev_b32_e32 v28, 16, v31
	v_and_b32_e32 v29, 0xffff0000, v31
	v_lshlrev_b32_e32 v30, 16, v32
	v_and_b32_e32 v31, 0xffff0000, v32
	v_lshlrev_b32_e32 v32, 16, v33
	v_and_b32_e32 v33, 0xffff0000, v33
	v_pk_fma_f32 v[28:29], v[152:153], v[16:17], v[28:29]
	v_pk_fma_f32 v[26:27], v[150:151], v[14:15], v[26:27]
	v_pk_fma_f32 v[32:33], v[140:141], v[12:13], v[32:33]
	v_pk_fma_f32 v[30:31], v[138:139], v[10:11], v[30:31]
	v_cvt_pk_bf16_f32 v26, v26, v27
	v_cvt_pk_bf16_f32 v27, v28, v29
	v_lshl_add_u64 v[138:139], v[4:5], 0, v[24:25]
	v_cvt_pk_bf16_f32 v28, v30, v31
	v_cvt_pk_bf16_f32 v29, v32, v33
	global_load_dwordx4 v[30:33], v[154:155], off offset:256
	s_waitcnt vmcnt(0)
	v_lshlrev_b32_e32 v4, 16, v30
	global_store_dwordx4 v[154:155], v[26:29], off sc1
	v_and_b32_e32 v5, 0xffff0000, v30
	v_lshlrev_b32_e32 v30, 16, v33
	v_lshlrev_b32_e32 v28, 16, v32
	v_and_b32_e32 v29, 0xffff0000, v32
	v_lshlrev_b32_e32 v26, 16, v31
	v_and_b32_e32 v27, 0xffff0000, v31
	v_and_b32_e32 v31, 0xffff0000, v33
	v_pk_fma_f32 v[28:29], v[126:127], v[6:7], v[28:29]
	v_pk_fma_f32 v[32:33], v[136:137], v[22:23], v[26:27]
	v_pk_fma_f32 v[4:5], v[134:135], v[20:21], v[4:5]
	v_pk_fma_f32 v[30:31], v[128:129], v[18:19], v[30:31]
	v_cvt_pk_bf16_f32 v26, v4, v5
	v_cvt_pk_bf16_f32 v27, v32, v33
	v_cvt_pk_bf16_f32 v28, v28, v29
	s_nop 0
	v_cvt_pk_bf16_f32 v29, v30, v31
	global_store_dwordx4 v[154:155], v[26:29], off offset:256 sc1
	global_load_dwordx4 v[26:29], v[138:139], off
	s_waitcnt vmcnt(0)
; __device__ __forceinline__ unsigned cvt_pk_bf16(float lo, float hi) { unsigned r; asm volatile("v_cvt_pk_bf16_f32 %0, %1, %2" : "=v"(r) : "v"(lo), "v"(hi)); return r; }
;     __device__ __forceinline__ void operator()(const f32x4 (&acc)[2][2][4][2], const Unit& u, int wr, int wc, int fr, int fq) const {
;     ...
; #pragma unroll
;             for (int ai = 0; ai < 2; ++ai)
; #pragma unroll
;                 for (int m = 0; m < 4; ++m) {
;                     const int row = row0 + ai * HALF + m * 16;
;                     bf16_t* xp = X + (size_t)row * DM + col0;
; #pragma unroll
;                     for (int bj = 0; bj < 2; ++bj) {
;                         f32x4 b0, b1;
;                         if (BASE16) { const u32x4 bv = *(const u32x4*)(xp + bj * HALF);
;                             b0 = (f32x4){__builtin_bit_cast(float, bv.x << 16), __builtin_bit_cast(float, bv.x & 0xffff0000u), __builtin_bit_cast(float, bv.y << 16), __builtin_bit_cast(float, bv.y & 0xffff0000u)};
;                             b1 = (f32x4){__builtin_bit_cast(float, bv.z << 16), __builtin_bit_cast(float, bv.z & 0xffff0000u), __builtin_bit_cast(float, bv.w << 16), __builtin_bit_cast(float, bv.w & 0xffff0000u)}; }
;                         else { const float* bp = base32 + (size_t)row * DM + col0 + bj * HALF; b0 = __builtin_nontemporal_load((const f32x4*)bp); b1 = __builtin_nontemporal_load((const f32x4*)(bp + 4)); }
;                         const f32x4 o0 = b0 + gg[bj][0] * acc[ai][bj][m][0], o1 = b1 + gg[bj][1] * acc[ai][bj][m][1];
;                         u32x4 w; w.x = cvt_pk_bf16(o0[0], o0[1]); w.y = cvt_pk_bf16(o0[2], o0[3]); w.z = cvt_pk_bf16(o1[0], o1[1]); w.w = cvt_pk_bf16(o1[2], o1[3]);
;                         *(u32x4*)(xp + bj * HALF) = w;
;                     }
;                     if (m & 1) asm volatile("" ::: "memory");
	v_lshlrev_b32_e32 v4, 16, v26
	v_and_b32_e32 v5, 0xffff0000, v26
	v_lshlrev_b32_e32 v26, 16, v27
	v_and_b32_e32 v27, 0xffff0000, v27
	v_lshlrev_b32_e32 v30, 16, v28
	v_and_b32_e32 v31, 0xffff0000, v28
	v_lshlrev_b32_e32 v28, 16, v29
	v_and_b32_e32 v29, 0xffff0000, v29
	v_pk_fma_f32 v[32:33], v[132:133], v[16:17], v[26:27]
	v_pk_fma_f32 v[124:125], v[124:125], v[12:13], v[28:29]
	v_pk_fma_f32 v[28:29], v[122:123], v[10:11], v[30:31]
	v_pk_fma_f32 v[4:5], v[130:131], v[14:15], v[4:5]
	v_lshl_add_u64 v[122:123], v[2:3], 0, v[24:25]
	v_cvt_pk_bf16_f32 v26, v4, v5
	v_cvt_pk_bf16_f32 v27, v32, v33
	v_cvt_pk_bf16_f32 v28, v28, v29
	v_cvt_pk_bf16_f32 v29, v124, v125
	global_load_dwordx4 v[30:33], v[138:139], off offset:256
	s_waitcnt vmcnt(0)
	v_lshlrev_b32_e32 v2, 16, v30
	global_store_dwordx4 v[138:139], v[26:29], off sc1
	v_and_b32_e32 v3, 0xffff0000, v30
	v_lshlrev_b32_e32 v4, 16, v31
	v_and_b32_e32 v5, 0xffff0000, v31
	v_lshlrev_b32_e32 v24, 16, v32
	v_and_b32_e32 v25, 0xffff0000, v32
	v_lshlrev_b32_e32 v26, 16, v33
	v_and_b32_e32 v27, 0xffff0000, v33
	v_pk_fma_f32 v[4:5], v[116:117], v[22:23], v[4:5]
	v_pk_fma_f32 v[2:3], v[114:115], v[20:21], v[2:3]
	v_pk_fma_f32 v[26:27], v[112:113], v[18:19], v[26:27]
	v_pk_fma_f32 v[24:25], v[110:111], v[6:7], v[24:25]
	v_cvt_pk_bf16_f32 v2, v2, v3
	v_cvt_pk_bf16_f32 v3, v4, v5
	v_add_co_u32_e32 v28, vcc, s70, v8
	v_cvt_pk_bf16_f32 v4, v24, v25
	v_cvt_pk_bf16_f32 v5, v26, v27
	global_load_dwordx4 v[24:27], v[122:123], off
	s_nop 0
	v_addc_co_u32_e32 v29, vcc, 0, v9, vcc
	global_store_dwordx4 v[138:139], v[2:5], off offset:256 sc1
	v_lshl_add_u64 v[30:31], v[8:9], 0, s[20:21]
	s_waitcnt vmcnt(1)
	v_lshlrev_b32_e32 v2, 16, v24
	v_and_b32_e32 v3, 0xffff0000, v24
	v_lshlrev_b32_e32 v4, 16, v25
	v_and_b32_e32 v5, 0xffff0000, v25
	v_lshlrev_b32_e32 v24, 16, v26
	v_and_b32_e32 v25, 0xffff0000, v26
	v_lshlrev_b32_e32 v26, 16, v27
	v_and_b32_e32 v27, 0xffff0000, v27
	v_pk_fma_f32 v[4:5], v[120:121], v[16:17], v[4:5]
	v_pk_fma_f32 v[2:3], v[118:119], v[14:15], v[2:3]
	v_pk_fma_f32 v[26:27], v[108:109], v[12:13], v[26:27]
	v_pk_fma_f32 v[24:25], v[106:107], v[10:11], v[24:25]
	v_cvt_pk_bf16_f32 v2, v2, v3
	v_cvt_pk_bf16_f32 v3, v4, v5
	s_nop 0
	v_cvt_pk_bf16_f32 v4, v24, v25
	v_cvt_pk_bf16_f32 v5, v26, v27
	global_load_dwordx4 v[24:27], v[122:123], off offset:256
	s_nop 0
	global_store_dwordx4 v[122:123], v[2:5], off sc1
	s_waitcnt vmcnt(1)
	s_nop 0
	v_lshlrev_b32_e32 v2, 16, v24
	v_and_b32_e32 v3, 0xffff0000, v24
	v_lshlrev_b32_e32 v4, 16, v25
	v_and_b32_e32 v5, 0xffff0000, v25
	v_lshlrev_b32_e32 v24, 16, v26
	v_and_b32_e32 v25, 0xffff0000, v26
	v_lshlrev_b32_e32 v26, 16, v27
	v_and_b32_e32 v27, 0xffff0000, v27
	v_pk_fma_f32 v[4:5], v[104:105], v[22:23], v[4:5]
	v_pk_fma_f32 v[2:3], v[102:103], v[20:21], v[2:3]
	v_pk_fma_f32 v[26:27], v[100:101], v[18:19], v[26:27]
	v_pk_fma_f32 v[24:25], v[98:99], v[6:7], v[24:25]
	v_cvt_pk_bf16_f32 v2, v2, v3
	v_cvt_pk_bf16_f32 v3, v4, v5
	s_nop 0
	v_cvt_pk_bf16_f32 v4, v24, v25
	v_cvt_pk_bf16_f32 v5, v26, v27
	global_store_dwordx4 v[122:123], v[2:5], off offset:256 sc1
	global_load_dwordx4 v[2:5], v[28:29], off
	s_waitcnt vmcnt(0)
	v_lshlrev_b32_e32 v24, 16, v2
	v_and_b32_e32 v25, 0xffff0000, v2
	v_lshlrev_b32_e32 v2, 16, v3
	v_and_b32_e32 v3, 0xffff0000, v3
	v_lshlrev_b32_e32 v26, 16, v4
	v_and_b32_e32 v27, 0xffff0000, v4
	v_lshlrev_b32_e32 v4, 16, v5
	v_and_b32_e32 v5, 0xffff0000, v5
	v_pk_fma_f32 v[32:33], v[96:97], v[16:17], v[2:3]
	v_pk_fma_f32 v[2:3], v[94:95], v[14:15], v[24:25]
	v_pk_fma_f32 v[24:25], v[92:93], v[12:13], v[4:5]
	v_pk_fma_f32 v[4:5], v[90:91], v[10:11], v[26:27]
	v_cvt_pk_bf16_f32 v2, v2, v3
	v_cvt_pk_bf16_f32 v3, v32, v33
	v_add_co_u32_e32 v32, vcc, s71, v8
	v_cvt_pk_bf16_f32 v4, v4, v5
	v_cvt_pk_bf16_f32 v5, v24, v25
	global_load_dwordx4 v[24:27], v[30:31], off offset:256
	s_nop 0
	v_addc_co_u32_e32 v33, vcc, 0, v9, vcc
	global_store_dwordx4 v[28:29], v[2:5], off sc1
	v_lshl_add_u64 v[28:29], v[8:9], 0, s[22:23]
	s_waitcnt vmcnt(1)
	v_lshlrev_b32_e32 v2, 16, v24
	v_and_b32_e32 v3, 0xffff0000, v24
	v_lshlrev_b32_e32 v4, 16, v25
	v_and_b32_e32 v5, 0xffff0000, v25
	v_lshlrev_b32_e32 v24, 16, v26
	v_and_b32_e32 v25, 0xffff0000, v26
	v_lshlrev_b32_e32 v26, 16, v27
	v_and_b32_e32 v27, 0xffff0000, v27
	v_pk_fma_f32 v[4:5], v[88:89], v[22:23], v[4:5]
	v_pk_fma_f32 v[2:3], v[86:87], v[20:21], v[2:3]
	v_pk_fma_f32 v[26:27], v[80:81], v[18:19], v[26:27]
	v_pk_fma_f32 v[24:25], v[78:79], v[6:7], v[24:25]
	v_cvt_pk_bf16_f32 v2, v2, v3
	v_cvt_pk_bf16_f32 v3, v4, v5
	s_nop 0
	v_cvt_pk_bf16_f32 v4, v24, v25
	v_cvt_pk_bf16_f32 v5, v26, v27
	global_load_dwordx4 v[24:27], v[32:33], off
	s_nop 0
	global_store_dwordx4 v[30:31], v[2:5], off offset:256 sc1
	v_add_co_u32_e32 v30, vcc, s72, v8
	s_waitcnt vmcnt(1)
; __device__ __forceinline__ unsigned cvt_pk_bf16(float lo, float hi) { unsigned r; asm volatile("v_cvt_pk_bf16_f32 %0, %1, %2" : "=v"(r) : "v"(lo), "v"(hi)); return r; }
;     __device__ __forceinline__ void operator()(const f32x4 (&acc)[2][2][4][2], const Unit& u, int wr, int wc, int fr, int fq) const {
;     ...
; #pragma unroll
;             for (int ai = 0; ai < 2; ++ai)
; #pragma unroll
;                 for (int m = 0; m < 4; ++m) {
;                     const int row = row0 + ai * HALF + m * 16;
;                     bf16_t* xp = X + (size_t)row * DM + col0;
; #pragma unroll
;                     for (int bj = 0; bj < 2; ++bj) {
;                         f32x4 b0, b1;
;                         if (BASE16) { const u32x4 bv = *(const u32x4*)(xp + bj * HALF);
;                             b0 = (f32x4){__builtin_bit_cast(float, bv.x << 16), __builtin_bit_cast(float, bv.x & 0xffff0000u), __builtin_bit_cast(float, bv.y << 16), __builtin_bit_cast(float, bv.y & 0xffff0000u)};
;                             b1 = (f32x4){__builtin_bit_cast(float, bv.z << 16), __builtin_bit_cast(float, bv.z & 0xffff0000u), __builtin_bit_cast(float, bv.w << 16), __builtin_bit_cast(float, bv.w & 0xffff0000u)}; }
;                         else { const float* bp = base32 + (size_t)row * DM + col0 + bj * HALF; b0 = __builtin_nontemporal_load((const f32x4*)bp); b1 = __builtin_nontemporal_load((const f32x4*)(bp + 4)); }
;                         const f32x4 o0 = b0 + gg[bj][0] * acc[ai][bj][m][0], o1 = b1 + gg[bj][1] * acc[ai][bj][m][1];
;                         u32x4 w; w.x = cvt_pk_bf16(o0[0], o0[1]); w.y = cvt_pk_bf16(o0[2], o0[3]); w.z = cvt_pk_bf16(o1[0], o1[1]); w.w = cvt_pk_bf16(o1[2], o1[3]);
;                         *(u32x4*)(xp + bj * HALF) = w;
;                     }
;                     if (m & 1) asm volatile("" ::: "memory");
	v_lshlrev_b32_e32 v2, 16, v24
	v_and_b32_e32 v3, 0xffff0000, v24
	v_lshlrev_b32_e32 v4, 16, v25
	v_and_b32_e32 v5, 0xffff0000, v25
	v_lshlrev_b32_e32 v24, 16, v26
	v_and_b32_e32 v25, 0xffff0000, v26
	v_lshlrev_b32_e32 v26, 16, v27
	v_and_b32_e32 v27, 0xffff0000, v27
	v_pk_fma_f32 v[4:5], v[84:85], v[16:17], v[4:5]
	v_pk_fma_f32 v[2:3], v[82:83], v[14:15], v[2:3]
	v_pk_fma_f32 v[26:27], v[76:77], v[12:13], v[26:27]
	v_pk_fma_f32 v[24:25], v[74:75], v[10:11], v[24:25]
	v_cvt_pk_bf16_f32 v2, v2, v3
	v_cvt_pk_bf16_f32 v3, v4, v5
	v_addc_co_u32_e32 v31, vcc, 0, v9, vcc
	v_cvt_pk_bf16_f32 v4, v24, v25
	v_cvt_pk_bf16_f32 v5, v26, v27
	global_load_dwordx4 v[24:27], v[28:29], off offset:256
	s_nop 0
	global_store_dwordx4 v[32:33], v[2:5], off sc1
	s_waitcnt vmcnt(1)
	s_nop 0
	v_lshlrev_b32_e32 v2, 16, v24
	v_and_b32_e32 v3, 0xffff0000, v24
	v_lshlrev_b32_e32 v4, 16, v25
	v_and_b32_e32 v5, 0xffff0000, v25
	v_lshlrev_b32_e32 v24, 16, v26
	v_and_b32_e32 v25, 0xffff0000, v26
	v_lshlrev_b32_e32 v26, 16, v27
	v_and_b32_e32 v27, 0xffff0000, v27
	v_pk_fma_f32 v[4:5], v[72:73], v[22:23], v[4:5]
	v_pk_fma_f32 v[2:3], v[70:71], v[20:21], v[2:3]
	v_pk_fma_f32 v[26:27], v[64:65], v[18:19], v[26:27]
	v_pk_fma_f32 v[24:25], v[62:63], v[6:7], v[24:25]
	v_cvt_pk_bf16_f32 v2, v2, v3
	v_cvt_pk_bf16_f32 v3, v4, v5
	s_nop 0
	v_cvt_pk_bf16_f32 v4, v24, v25
	v_cvt_pk_bf16_f32 v5, v26, v27
	global_store_dwordx4 v[28:29], v[2:5], off offset:256 sc1
	global_load_dwordx4 v[2:5], v[30:31], off
	v_lshl_add_u64 v[28:29], v[8:9], 0, s[24:25]
	s_waitcnt vmcnt(0)
	v_lshlrev_b32_e32 v24, 16, v2
	v_and_b32_e32 v25, 0xffff0000, v2
	v_lshlrev_b32_e32 v2, 16, v3
	v_and_b32_e32 v3, 0xffff0000, v3
	v_lshlrev_b32_e32 v26, 16, v4
	v_and_b32_e32 v27, 0xffff0000, v4
	v_lshlrev_b32_e32 v4, 16, v5
	v_and_b32_e32 v5, 0xffff0000, v5
	v_pk_fma_f32 v[32:33], v[68:69], v[16:17], v[2:3]
	v_pk_fma_f32 v[2:3], v[66:67], v[14:15], v[24:25]
	v_pk_fma_f32 v[24:25], v[60:61], v[12:13], v[4:5]
	v_pk_fma_f32 v[4:5], v[58:59], v[10:11], v[26:27]
	v_cvt_pk_bf16_f32 v2, v2, v3
	v_cvt_pk_bf16_f32 v3, v32, v33
	v_add_co_u32_e32 v32, vcc, s73, v8
	v_cvt_pk_bf16_f32 v4, v4, v5
	v_cvt_pk_bf16_f32 v5, v24, v25
	global_load_dwordx4 v[24:27], v[28:29], off offset:256
	s_nop 0
	v_addc_co_u32_e32 v33, vcc, 0, v9, vcc
	global_store_dwordx4 v[30:31], v[2:5], off sc1
	v_lshl_add_u64 v[30:31], v[8:9], 0, s[4:5]
	s_waitcnt vmcnt(1)
	v_lshlrev_b32_e32 v2, 16, v24
	v_and_b32_e32 v3, 0xffff0000, v24
	v_lshlrev_b32_e32 v4, 16, v25
	v_and_b32_e32 v5, 0xffff0000, v25
	v_lshlrev_b32_e32 v24, 16, v26
	v_and_b32_e32 v25, 0xffff0000, v26
	v_lshlrev_b32_e32 v26, 16, v27
	v_and_b32_e32 v27, 0xffff0000, v27
	v_pk_fma_f32 v[4:5], v[56:57], v[22:23], v[4:5]
	v_pk_fma_f32 v[2:3], v[54:55], v[20:21], v[2:3]
	v_pk_fma_f32 v[26:27], v[48:49], v[18:19], v[26:27]
	v_pk_fma_f32 v[24:25], v[46:47], v[6:7], v[24:25]
	v_cvt_pk_bf16_f32 v2, v2, v3
	v_cvt_pk_bf16_f32 v3, v4, v5
	s_nop 0
	v_cvt_pk_bf16_f32 v4, v24, v25
	v_cvt_pk_bf16_f32 v5, v26, v27
	global_load_dwordx4 v[24:27], v[32:33], off
	s_waitcnt vmcnt(0)
	v_lshlrev_b32_e32 v8, 16, v26
	global_store_dwordx4 v[28:29], v[2:5], off offset:256 sc1
	v_and_b32_e32 v9, 0xffff0000, v26
	v_pk_fma_f32 v[8:9], v[42:43], v[10:11], v[8:9]
	v_lshlrev_b32_e32 v2, 16, v24
	v_and_b32_e32 v3, 0xffff0000, v24
	v_lshlrev_b32_e32 v4, 16, v25
	v_and_b32_e32 v5, 0xffff0000, v25
	v_lshlrev_b32_e32 v24, 16, v27
	v_and_b32_e32 v25, 0xffff0000, v27
	v_pk_fma_f32 v[4:5], v[52:53], v[16:17], v[4:5]
	v_pk_fma_f32 v[2:3], v[50:51], v[14:15], v[2:3]
	v_pk_fma_f32 v[12:13], v[44:45], v[12:13], v[24:25]
	v_cvt_pk_bf16_f32 v2, v2, v3
	v_cvt_pk_bf16_f32 v3, v4, v5
	v_cvt_pk_bf16_f32 v4, v8, v9
	s_nop 0
	v_cvt_pk_bf16_f32 v5, v12, v13
	global_load_dwordx4 v[8:11], v[30:31], off offset:256
	s_nop 0
	global_store_dwordx4 v[32:33], v[2:5], off sc1
	s_waitcnt vmcnt(1)
	s_nop 0
	v_lshlrev_b32_e32 v2, 16, v8
	v_and_b32_e32 v3, 0xffff0000, v8
	v_lshlrev_b32_e32 v4, 16, v9
	v_and_b32_e32 v5, 0xffff0000, v9
	v_lshlrev_b32_e32 v8, 16, v10
	v_and_b32_e32 v9, 0xffff0000, v10
	v_lshlrev_b32_e32 v10, 16, v11
	v_and_b32_e32 v11, 0xffff0000, v11
	v_pk_fma_f32 v[4:5], v[40:41], v[22:23], v[4:5]
	v_pk_fma_f32 v[2:3], v[38:39], v[20:21], v[2:3]
	v_pk_fma_f32 v[10:11], v[36:37], v[18:19], v[10:11]
	v_pk_fma_f32 v[6:7], v[34:35], v[6:7], v[8:9]
	v_cvt_pk_bf16_f32 v2, v2, v3
	v_cvt_pk_bf16_f32 v3, v4, v5
	s_nop 0
	v_cvt_pk_bf16_f32 v4, v6, v7
	v_cvt_pk_bf16_f32 v5, v10, v11
	global_store_dwordx4 v[30:31], v[2:5], off offset:256 sc1
	s_and_b64 vcc, exec, s[2:3]
	s_mov_b64 s[2:3], -1
	s_cbranch_vccnz .LBB0_1501

; __global__ void __launch_bounds__(NWAVES * 64, 2) mk_fwd(Args args) {
	.amdhsa_kernel _Z6mk_fwd4Args
		.amdhsa_group_segment_fixed_size 0
		.amdhsa_private_segment_fixed_size 0
		.amdhsa_kernarg_size 464
		.amdhsa_user_sgpr_count 2
		.amdhsa_user_sgpr_dispatch_ptr 0
		.amdhsa_user_sgpr_queue_ptr 0
		.amdhsa_user_sgpr_kernarg_segment_ptr 1
		.amdhsa_user_sgpr_dispatch_id 0
		.amdhsa_user_sgpr_kernarg_preload_length 0
		.amdhsa_user_sgpr_kernarg_preload_offset 0
		.amdhsa_user_sgpr_private_segment_size 0
		.amdhsa_uses_dynamic_stack 0
		.amdhsa_enable_private_segment 0
		.amdhsa_system_sgpr_workgroup_id_x 1
		.amdhsa_system_sgpr_workgroup_id_y 0
		.amdhsa_system_sgpr_workgroup_id_z 0
		.amdhsa_system_sgpr_workgroup_info 0
		.amdhsa_system_vgpr_workitem_id 0
		.amdhsa_next_free_vgpr 254
		.amdhsa_next_free_sgpr 98
		.amdhsa_accum_offset 256
		.amdhsa_reserve_vcc 1
		.amdhsa_float_round_mode_32 0
		.amdhsa_float_round_mode_16_64 0
		.amdhsa_float_denorm_mode_32 3
		.amdhsa_float_denorm_mode_16_64 3
		.amdhsa_dx10_clamp 1
		.amdhsa_ieee_mode 1
		.amdhsa_fp16_overflow 0
		.amdhsa_tg_split 0
		.amdhsa_exception_fp_ieee_invalid_op 0
		.amdhsa_exception_fp_denorm_src 0
		.amdhsa_exception_fp_ieee_div_zero 0
		.amdhsa_exception_fp_ieee_overflow 0
		.amdhsa_exception_fp_ieee_underflow 0
		.amdhsa_exception_fp_ieee_inexact 0
		.amdhsa_exception_int_div_zero 0
	.end_amdhsa_kernel

; __global__ void __launch_bounds__(NWAVES * 64, 2) mk_fwd(Args args) {
amdhsa.kernels:
  - .agpr_count:     0
    .args:
      - .offset:         0
        .size:           208
        .value_kind:     by_value
      - .offset:         208
        .size:           4
        .value_kind:     hidden_block_count_x
      - .offset:         212
        .size:           4
        .value_kind:     hidden_block_count_y
      - .offset:         216
        .size:           4
        .value_kind:     hidden_block_count_z
      - .offset:         220
        .size:           2
        .value_kind:     hidden_group_size_x
      - .offset:         222
        .size:           2
        .value_kind:     hidden_group_size_y
      - .offset:         224
        .size:           2
        .value_kind:     hidden_group_size_z
      - .offset:         226
        .size:           2
        .value_kind:     hidden_remainder_x
      - .offset:         228
        .size:           2
        .value_kind:     hidden_remainder_y
      - .offset:         230
        .size:           2
        .value_kind:     hidden_remainder_z
      - .offset:         248
        .size:           8
        .value_kind:     hidden_global_offset_x
      - .offset:         256
        .size:           8
        .value_kind:     hidden_global_offset_y
      - .offset:         264
        .size:           8
        .value_kind:     hidden_global_offset_z
      - .offset:         272
        .size:           2
        .value_kind:     hidden_grid_dims
      - .offset:         328
        .size:           4
        .value_kind:     hidden_dynamic_lds_size
    .group_segment_fixed_size: 0
    .kernarg_segment_align: 8
    .kernarg_segment_size: 464
    .language:       OpenCL C
    .language_version:
      - 2
      - 0
    .max_flat_workgroup_size: 512
    .name:           _Z6mk_fwd4Args
    .private_segment_fixed_size: 0
    .sgpr_count:     104
    .sgpr_spill_count: 194
    .symbol:         _Z6mk_fwd4Args.kd
    .uniform_work_group_size: 1
    .uses_dynamic_stack: false
    .vgpr_count:     254
    .vgpr_spill_count: 0
    .wavefront_size: 64
